# MLA loop: 3-slot LDS tile ring so one barrier per tile instead of two (on top of v37 stack)
# speedup vs baseline: 1.0153x; 1.0153x over previous
; __device__ __forceinline__ int crow(int r, int hi) { return (r & 3) + 8 * (r >> 2) + 4 * hi; }
; __device__ __forceinline__ unsigned cvtpk(float lo, float hi) { unsigned r; asm volatile("v_cvt_pk_bf16_f32 %0, %1, %2" : "=v"(r) : "v"(lo), "v"(hi)); return r; }
; #define RESC(a) do { if (__any((a) < 1.f)) { if (hi == 0) al_l[r32] = (a); asm volatile("s_waitcnt lgkmcnt(0)" ::: "memory"); \
;     _Pragma("unroll") for (int d = 0; d < 4; ++d) _Pragma("unroll") for (int r = 0; r < 16; ++r) o[d][r] *= al_l[crow(r, hi)]; } } while (0)
; #define RESC(a) do { if (__any((a) < 1.f)) { if (hi == 0) al_l[r32] = (a); asm volatile("s_waitcnt lgkmcnt(0)" ::: "memory"); \
;     _Pragma("unroll") for (int d = 0; d < 4; ++d) _Pragma("unroll") for (int r = 0; r < 16; ++r) o[d][r] *= al_l[crow(r, hi)]; } } while (0)
; #define RESC(a) do { if (__any((a) < 1.f)) { if (hi == 0) al_l[r32] = (a); asm volatile("s_waitcnt lgkmcnt(0)" ::: "memory"); \
;     _Pragma("unroll") for (int d = 0; d < 4; ++d) _Pragma("unroll") for (int r = 0; r < 16; ++r) o[d][r] *= al_l[crow(r, hi)]; } } while (0)
; __device__ __forceinline__ void attn_unit7(const unsigned char* __restrict__ Q8, int ldq, const unsigned char* __restrict__ Kn8, int ldk, const unsigned char* __restrict__ Kr8, ...
;     ...
;   qkt9(pB0, pB1, Kn_lds + 8192, Kr_lds + 4096, qf, 7.0f - m_reg, r32, hi);
;   finishSM9(pA0, pA1, alA, l_reg, p8);
;   pv8(o, Vt_lds, p8, r32, hi); partialSM9(pB0, pB1, m_reg, alB, thr_raw);
;   RESC(alB);
;   finishSM9(pB0, pB1, alB, l_reg, p8);
;   pv8(o, Vt_lds + 8192, p8, r32, hi);
;   if (hi == 0) li_l[r32] = l_reg; asm volatile("s_waitcnt lgkmcnt(0)" ::: "memory");
;   char* ost = lds + G8_LDS + wid * 8192;
; #pragma unroll
;   for (int r = 0; r < 16; ++r) { const int orow = crow(r, hi); const float rl = __builtin_amdgcn_rcpf(li_l[orow]);
; #pragma unroll
;     for (int d0 = 0; d0 < 4; ++d0) *(bf16_t*)(ost + orow * 256 + (d0 * 32 + r32) * 2) = (bf16_t)(cvtpk(o[d0][r] * rl, 0.f) & 0xffffu); }
;   asm volatile("s_waitcnt lgkmcnt(0)" ::: "memory");
.LBB0_1310:
	s_or_b64 exec, exec, s[16:17]
	v_mov_b32_e32 v124, v1
	v_mov_b32_e32 v128, v1
	v_mov_b32_e32 v125, v1
	v_mov_b32_e32 v129, v1
	v_mov_b32_e32 v126, v1
	v_mov_b32_e32 v130, v1
	v_mov_b32_e32 v127, v1
	v_mov_b32_e32 v131, v1
	v_cvt_pk_fp8_f32 v124, v139, v141
	v_cvt_pk_fp8_f32 v128, v133, v136
	v_cvt_pk_fp8_f32 v125, v140, v142
	v_cvt_pk_fp8_f32 v129, v134, v137
	v_cvt_pk_fp8_f32 v126, v120, v122
	v_cvt_pk_fp8_f32 v130, v103, v107
	v_cvt_pk_fp8_f32 v127, v121, v110
	v_cvt_pk_fp8_f32 v131, v104, v108
	v_cvt_pk_fp8_f32 v124, v114, v116 op_sel:[0,0,1]
	v_cvt_pk_fp8_f32 v128, v115, v117 op_sel:[0,0,1]
	v_cvt_pk_fp8_f32 v125, v119, v138 op_sel:[0,0,1]
	v_cvt_pk_fp8_f32 v129, v118, v135 op_sel:[0,0,1]
	v_cvt_pk_fp8_f32 v126, v98, v100 op_sel:[0,0,1]
	v_cvt_pk_fp8_f32 v130, v99, v101 op_sel:[0,0,1]
	v_cvt_pk_fp8_f32 v127, v105, v109 op_sel:[0,0,1]
	v_cvt_pk_fp8_f32 v131, v102, v106 op_sel:[0,0,1]
	s_waitcnt lgkmcnt(0)
	v_add_u32_e32 v0, v187, v207
	s_lshl_b32 s16, s29, 12
	s_waitcnt lgkmcnt(5)
	v_mfma_scale_f32_32x32x64_f8f6f4 v[50:65], v[124:131], v[90:97], v[50:65], v194, v194 op_sel_hi:[0,0,0]
	s_add_u32 s16, s27, s16
	s_addc_u32 s17, s28, 0
	s_lshl_b64 s[14:15], s[14:15], 1
	s_add_u32 s14, s16, s14
	s_addc_u32 s15, s17, s15
	s_add_i32 s3, s3, s2
	s_cmpk_gt_i32 s3, 0x3ff
	s_waitcnt lgkmcnt(4)
	v_mfma_scale_f32_32x32x64_f8f6f4 v[34:49], v[124:131], v[82:89], v[34:49], v194, v194 op_sel_hi:[0,0,0]
	s_waitcnt lgkmcnt(1)
	v_mfma_scale_f32_32x32x64_f8f6f4 v[18:33], v[124:131], v[74:81], v[18:33], v194, v194 op_sel_hi:[0,0,0]
	ds_read_b32 v74, v0 offset:40960
	v_lshl_add_u32 v75, v182, 13, 0
	v_lshlrev_b32_e32 v76, 1, v183
	v_lshlrev_b32_e32 v77, 10, v175
	v_add3_u32 v76, v75, v76, v77
	s_waitcnt lgkmcnt(0)
	s_barrier
	v_rcp_f32_e32 v74, v74
	s_nop 1
	v_mul_f32_e32 v50, v50, v74
	s_nop 7
	v_mul_f32_e32 v34, v34, v74
	v_cvt_pk_bf16_f32 v50, v50, v1
	ds_write_b16 v76, v50 offset:43008
	v_cvt_pk_bf16_f32 v34, v34, v1
	ds_write_b16 v76, v34 offset:43072
	v_mfma_scale_f32_32x32x64_f8f6f4 v[2:17], v[124:131], v[66:73], v[2:17], v194, v194 op_sel_hi:[0,0,0]
	v_mul_f32_e32 v18, v18, v74
	v_cvt_pk_bf16_f32 v18, v18, v1
	ds_write_b16 v76, v18 offset:43136
	s_nop 15
	s_nop 1
	v_mul_f32_e32 v2, v2, v74
	v_cvt_pk_bf16_f32 v2, v2, v1
	ds_read_b32 v18, v0 offset:40964
	ds_write_b16 v76, v2 offset:43200
	s_waitcnt lgkmcnt(1)
	v_rcp_f32_e32 v18, v18
	s_nop 0
	v_mul_f32_e32 v2, v51, v18
	v_cvt_pk_bf16_f32 v2, v2, v1
	ds_write_b16 v76, v2 offset:43264
	v_mul_f32_e32 v2, v35, v18
	v_cvt_pk_bf16_f32 v2, v2, v1
	ds_write_b16 v76, v2 offset:43328
	v_mul_f32_e32 v2, v19, v18
	v_cvt_pk_bf16_f32 v2, v2, v1
	ds_write_b16 v76, v2 offset:43392
	v_mul_f32_e32 v2, v3, v18
	v_cvt_pk_bf16_f32 v2, v2, v1
	ds_read_b32 v3, v0 offset:40968
	ds_write_b16 v76, v2 offset:43456
	s_waitcnt lgkmcnt(1)
	v_rcp_f32_e32 v3, v3
	s_nop 0
	v_mul_f32_e32 v2, v52, v3
	v_cvt_pk_bf16_f32 v2, v2, v1
	ds_write_b16 v76, v2 offset:43520
	v_mul_f32_e32 v2, v36, v3
	v_cvt_pk_bf16_f32 v2, v2, v1
	ds_write_b16 v76, v2 offset:43584
	v_mul_f32_e32 v2, v20, v3
	v_cvt_pk_bf16_f32 v2, v2, v1
	ds_write_b16 v76, v2 offset:43648
	v_mul_f32_e32 v2, v4, v3
	v_cvt_pk_bf16_f32 v2, v2, v1
	ds_read_b32 v3, v0 offset:40972
	ds_write_b16 v76, v2 offset:43712
	s_waitcnt lgkmcnt(1)
	v_rcp_f32_e32 v3, v3
	s_nop 0
	v_mul_f32_e32 v2, v53, v3
	v_cvt_pk_bf16_f32 v2, v2, v1
	ds_write_b16 v76, v2 offset:43776
	v_mul_f32_e32 v2, v37, v3
	v_cvt_pk_bf16_f32 v2, v2, v1
	ds_write_b16 v76, v2 offset:43840
	v_mul_f32_e32 v2, v21, v3
	v_cvt_pk_bf16_f32 v2, v2, v1
	ds_write_b16 v76, v2 offset:43904
	v_mul_f32_e32 v2, v5, v3
	v_cvt_pk_bf16_f32 v2, v2, v1
	ds_read_b32 v3, v0 offset:40992
	ds_write_b16 v76, v2 offset:43968
	s_waitcnt lgkmcnt(1)
	v_rcp_f32_e32 v3, v3
	s_nop 0
	v_mul_f32_e32 v2, v54, v3
	v_cvt_pk_bf16_f32 v2, v2, v1
	ds_write_b16 v76, v2 offset:45056
	v_mul_f32_e32 v2, v38, v3
	v_cvt_pk_bf16_f32 v2, v2, v1
	ds_write_b16 v76, v2 offset:45120
	v_mul_f32_e32 v2, v22, v3
	v_cvt_pk_bf16_f32 v2, v2, v1
	ds_write_b16 v76, v2 offset:45184
	v_mul_f32_e32 v2, v6, v3
	v_cvt_pk_bf16_f32 v2, v2, v1
	ds_read_b32 v3, v0 offset:40996
	ds_write_b16 v76, v2 offset:45248
	s_waitcnt lgkmcnt(1)
	v_rcp_f32_e32 v3, v3
	s_nop 0
	v_mul_f32_e32 v2, v55, v3
	v_cvt_pk_bf16_f32 v2, v2, v1
	ds_write_b16 v76, v2 offset:45312
	v_mul_f32_e32 v2, v39, v3
	v_cvt_pk_bf16_f32 v2, v2, v1
	ds_write_b16 v76, v2 offset:45376
	v_mul_f32_e32 v2, v23, v3
	v_cvt_pk_bf16_f32 v2, v2, v1
	ds_write_b16 v76, v2 offset:45440
	v_mul_f32_e32 v2, v7, v3
	v_cvt_pk_bf16_f32 v2, v2, v1
	ds_read_b32 v3, v0 offset:41000
	ds_write_b16 v76, v2 offset:45504
	s_waitcnt lgkmcnt(1)
	v_rcp_f32_e32 v3, v3
	s_nop 0
	v_mul_f32_e32 v2, v56, v3
	v_cvt_pk_bf16_f32 v2, v2, v1
	ds_write_b16 v76, v2 offset:45568
	v_mul_f32_e32 v2, v40, v3
	v_cvt_pk_bf16_f32 v2, v2, v1
	ds_write_b16 v76, v2 offset:45632
	v_mul_f32_e32 v2, v24, v3
	v_cvt_pk_bf16_f32 v2, v2, v1
	ds_write_b16 v76, v2 offset:45696
	v_mul_f32_e32 v2, v8, v3
	v_cvt_pk_bf16_f32 v2, v2, v1
	ds_read_b32 v3, v0 offset:41004
	ds_write_b16 v76, v2 offset:45760
	s_waitcnt lgkmcnt(1)
	v_rcp_f32_e32 v3, v3
	s_nop 0
	v_mul_f32_e32 v2, v57, v3
	v_cvt_pk_bf16_f32 v2, v2, v1
	ds_write_b16 v76, v2 offset:45824
	v_mul_f32_e32 v2, v41, v3
	v_cvt_pk_bf16_f32 v2, v2, v1
	ds_write_b16 v76, v2 offset:45888
	v_mul_f32_e32 v2, v25, v3
	v_cvt_pk_bf16_f32 v2, v2, v1
	ds_write_b16 v76, v2 offset:45952
	v_mul_f32_e32 v2, v9, v3
	v_cvt_pk_bf16_f32 v2, v2, v1
	ds_read_b32 v3, v0 offset:41024
	ds_write_b16 v76, v2 offset:46016
	s_waitcnt lgkmcnt(1)
; __device__ __forceinline__ int crow(int r, int hi) { return (r & 3) + 8 * (r >> 2) + 4 * hi; }
; __device__ __forceinline__ unsigned cvtpk(float lo, float hi) { unsigned r; asm volatile("v_cvt_pk_bf16_f32 %0, %1, %2" : "=v"(r) : "v"(lo), "v"(hi)); return r; }
; __device__ __forceinline__ void attn_unit7(const unsigned char* __restrict__ Q8, int ldq, const unsigned char* __restrict__ Kn8, int ldk, const unsigned char* __restrict__ Kr8, ...
;     ...
;   for (int r = 0; r < 16; ++r) { const int orow = crow(r, hi); const float rl = __builtin_amdgcn_rcpf(li_l[orow]);
; #pragma unroll
;     for (int d0 = 0; d0 < 4; ++d0) *(bf16_t*)(ost + orow * 256 + (d0 * 32 + r32) * 2) = (bf16_t)(cvtpk(o[d0][r] * rl, 0.f) & 0xffffu); }
;   asm volatile("s_waitcnt lgkmcnt(0)" ::: "memory");
;   { bf16_t* Og = Ob + (unsigned)(wid * 32 * ldo);
; #pragma unroll
;     for (int i = 0; i < 8; ++i) { const int q = i * 64 + lane, row = q >> 4, c16 = q & 15;
;       *(u32x4*)(Og + (unsigned)(row * ldo + c16 * 8)) = *(const u32x4*)(ost + row * 256 + c16 * 16); } }
;   __syncthreads();
	v_rcp_f32_e32 v3, v3
	s_nop 0
	v_mul_f32_e32 v2, v58, v3
	v_cvt_pk_bf16_f32 v2, v2, v1
	ds_write_b16 v76, v2 offset:47104
	v_mul_f32_e32 v2, v42, v3
	v_cvt_pk_bf16_f32 v2, v2, v1
	ds_write_b16 v76, v2 offset:47168
	v_mul_f32_e32 v2, v26, v3
	v_cvt_pk_bf16_f32 v2, v2, v1
	ds_write_b16 v76, v2 offset:47232
	v_mul_f32_e32 v2, v10, v3
	v_cvt_pk_bf16_f32 v2, v2, v1
	ds_read_b32 v3, v0 offset:41028
	ds_write_b16 v76, v2 offset:47296
	s_waitcnt lgkmcnt(1)
	v_rcp_f32_e32 v3, v3
	s_nop 0
	v_mul_f32_e32 v2, v59, v3
	v_cvt_pk_bf16_f32 v2, v2, v1
	ds_write_b16 v76, v2 offset:47360
	v_mul_f32_e32 v2, v43, v3
	v_cvt_pk_bf16_f32 v2, v2, v1
	ds_write_b16 v76, v2 offset:47424
	v_mul_f32_e32 v2, v27, v3
	v_cvt_pk_bf16_f32 v2, v2, v1
	ds_write_b16 v76, v2 offset:47488
	v_mul_f32_e32 v2, v11, v3
	v_cvt_pk_bf16_f32 v2, v2, v1
	ds_read_b32 v3, v0 offset:41032
	ds_write_b16 v76, v2 offset:47552
	s_waitcnt lgkmcnt(1)
	v_rcp_f32_e32 v3, v3
	s_nop 0
	v_mul_f32_e32 v2, v60, v3
	v_cvt_pk_bf16_f32 v2, v2, v1
	ds_write_b16 v76, v2 offset:47616
	v_mul_f32_e32 v2, v44, v3
	v_cvt_pk_bf16_f32 v2, v2, v1
	ds_write_b16 v76, v2 offset:47680
	v_mul_f32_e32 v2, v28, v3
	v_cvt_pk_bf16_f32 v2, v2, v1
	ds_write_b16 v76, v2 offset:47744
	v_mul_f32_e32 v2, v12, v3
	v_cvt_pk_bf16_f32 v2, v2, v1
	ds_read_b32 v3, v0 offset:41036
	ds_write_b16 v76, v2 offset:47808
	s_waitcnt lgkmcnt(1)
	v_rcp_f32_e32 v3, v3
	s_nop 0
	v_mul_f32_e32 v2, v61, v3
	v_cvt_pk_bf16_f32 v2, v2, v1
	ds_write_b16 v76, v2 offset:47872
	v_mul_f32_e32 v2, v45, v3
	v_cvt_pk_bf16_f32 v2, v2, v1
	ds_write_b16 v76, v2 offset:47936
	v_mul_f32_e32 v2, v29, v3
	v_cvt_pk_bf16_f32 v2, v2, v1
	ds_write_b16 v76, v2 offset:48000
	v_mul_f32_e32 v2, v13, v3
	v_cvt_pk_bf16_f32 v2, v2, v1
	ds_read_b32 v3, v0 offset:41056
	ds_write_b16 v76, v2 offset:48064
	s_waitcnt lgkmcnt(1)
	v_rcp_f32_e32 v3, v3
	s_nop 0
	v_mul_f32_e32 v2, v62, v3
	v_cvt_pk_bf16_f32 v2, v2, v1
	ds_write_b16 v76, v2 offset:49152
	v_mul_f32_e32 v2, v46, v3
	v_cvt_pk_bf16_f32 v2, v2, v1
	ds_write_b16 v76, v2 offset:49216
	v_mul_f32_e32 v2, v30, v3
	v_cvt_pk_bf16_f32 v2, v2, v1
	ds_write_b16 v76, v2 offset:49280
	v_mul_f32_e32 v2, v14, v3
	v_cvt_pk_bf16_f32 v2, v2, v1
	ds_read_b32 v3, v0 offset:41060
	ds_write_b16 v76, v2 offset:49344
	v_and_b32_e32 v14, 0xf0, v174
	s_waitcnt lgkmcnt(1)
	v_rcp_f32_e32 v3, v3
	s_nop 0
	v_mul_f32_e32 v2, v63, v3
	v_cvt_pk_bf16_f32 v2, v2, v1
	ds_write_b16 v76, v2 offset:49408
	v_mul_f32_e32 v2, v47, v3
	v_cvt_pk_bf16_f32 v2, v2, v1
	ds_write_b16 v76, v2 offset:49472
	v_mul_f32_e32 v2, v31, v3
	v_cvt_pk_bf16_f32 v2, v2, v1
	ds_write_b16 v76, v2 offset:49536
	v_mul_f32_e32 v2, v15, v3
	v_cvt_pk_bf16_f32 v2, v2, v1
	ds_read_b32 v3, v0 offset:41064
	ds_write_b16 v76, v2 offset:49600
	v_add_u32_e32 v15, v75, v14
	s_waitcnt lgkmcnt(1)
	v_rcp_f32_e32 v3, v3
	s_nop 0
	v_mul_f32_e32 v2, v64, v3
	v_cvt_pk_bf16_f32 v2, v2, v1
	ds_write_b16 v76, v2 offset:49664
	v_mul_f32_e32 v2, v48, v3
	v_cvt_pk_bf16_f32 v2, v2, v1
	ds_write_b16 v76, v2 offset:49728
	v_mul_f32_e32 v2, v32, v3
	v_cvt_pk_bf16_f32 v2, v2, v1
	ds_write_b16 v76, v2 offset:49792
	v_mul_f32_e32 v2, v16, v3
	v_cvt_pk_bf16_f32 v2, v2, v1
	ds_read_b32 v0, v0 offset:41068
	ds_write_b16 v76, v2 offset:49856
	v_lshrrev_b32_e32 v16, 4, v184
	s_waitcnt lgkmcnt(1)
	v_rcp_f32_e32 v0, v0
	s_nop 0
	v_mul_f32_e32 v2, v65, v0
	v_cvt_pk_bf16_f32 v2, v2, v1
	ds_write_b16 v76, v2 offset:49920
	v_mul_f32_e32 v2, v49, v0
	v_cvt_pk_bf16_f32 v2, v2, v1
	ds_write_b16 v76, v2 offset:49984
	v_mul_f32_e32 v2, v33, v0
	v_mul_f32_e32 v0, v17, v0
	v_cvt_pk_bf16_f32 v2, v2, v1
	ds_write_b16 v76, v2 offset:50048
	v_cvt_pk_bf16_f32 v0, v0, v1
	ds_write_b16 v76, v0 offset:50112
	v_lshlrev_b32_e32 v0, 16, v182
	s_waitcnt lgkmcnt(0)
	v_lshl_add_u64 v[10:11], v[0:1], 1, s[14:15]
	v_lshl_add_u32 v0, v16, 8, v15
	v_or_b32_e32 v17, 4, v16
	ds_read_b128 v[2:5], v0 offset:43008
	v_lshl_add_u32 v6, v17, 8, v15
	ds_read_b128 v[6:9], v6 offset:43008
	v_lshl_or_b32 v0, v16, 12, v14
	v_lshl_add_u64 v[12:13], v[10:11], 0, v[0:1]
	v_lshl_or_b32 v0, v17, 12, v14
	s_waitcnt lgkmcnt(1)
	flat_store_dwordx4 v[12:13], v[2:5]
	v_or_b32_e32 v17, 12, v16
	s_nop 0
	v_lshl_add_u64 v[2:3], v[10:11], 0, v[0:1]
	v_or_b32_e32 v0, 8, v16
	s_waitcnt lgkmcnt(0)
	flat_store_dwordx4 v[2:3], v[6:9]
	v_lshl_add_u32 v2, v0, 8, v15
	ds_read_b128 v[2:5], v2 offset:43008
	v_lshl_add_u32 v6, v17, 8, v15
	ds_read_b128 v[6:9], v6 offset:43008
	v_lshl_or_b32 v0, v0, 12, v14
	v_lshl_add_u64 v[12:13], v[10:11], 0, v[0:1]
	v_lshl_or_b32 v0, v17, 12, v14
	s_waitcnt lgkmcnt(0)
	flat_store_dwordx4 v[12:13], v[2:5]
	v_or_b32_e32 v17, 20, v16
	s_nop 0
	v_lshl_add_u64 v[2:3], v[10:11], 0, v[0:1]
	v_or_b32_e32 v0, 16, v16
	flat_store_dwordx4 v[2:3], v[6:9]
	v_lshl_add_u32 v2, v0, 8, v15
	ds_read_b128 v[2:5], v2 offset:43008
	v_lshl_add_u32 v6, v17, 8, v15
	ds_read_b128 v[6:9], v6 offset:43008
	v_lshl_or_b32 v0, v0, 12, v14
	v_lshl_add_u64 v[12:13], v[10:11], 0, v[0:1]
	v_lshl_or_b32 v0, v17, 12, v14
	s_waitcnt lgkmcnt(0)
	flat_store_dwordx4 v[12:13], v[2:5]
	s_nop 1
	v_lshl_add_u64 v[2:3], v[10:11], 0, v[0:1]
	v_or_b32_e32 v0, 24, v16
	flat_store_dwordx4 v[2:3], v[6:9]
	v_lshl_add_u32 v2, v0, 8, v15
	v_or_b32_e32 v16, 28, v16
	ds_read_b128 v[2:5], v2 offset:43008
	v_lshl_add_u32 v6, v16, 8, v15
	ds_read_b128 v[6:9], v6 offset:43008
	v_lshl_or_b32 v0, v0, 12, v14
	v_lshl_add_u64 v[12:13], v[10:11], 0, v[0:1]
	v_lshl_or_b32 v0, v16, 12, v14
	s_waitcnt lgkmcnt(0)
	flat_store_dwordx4 v[12:13], v[2:5]
	s_nop 1
	v_lshl_add_u64 v[2:3], v[10:11], 0, v[0:1]
	flat_store_dwordx4 v[2:3], v[6:9]
	s_waitcnt lgkmcnt(0)
	s_barrier
	s_cbranch_scc1 .LBB0_1352

; #define SLOAD() do { vs0 = *(const bf16x8*)(Vh + voff); vs1 = *(const bf16x8*)(Vh + voff + 32u * (unsigned)ldv); \
;     ks0 = *(const bf16x8*)(Kh + koff); ks1 = *(const bf16x8*)(Kh + koff + 32u * (unsigned)ldk); \
;     if constexpr (NR > 0) { kr = *(const bf16x8*)(Krh + kroff); kroff += 64u * 64u; } voff += 64u * (unsigned)ldv; koff += 64u * (unsigned)ldk; } while (0)
; #define SWRITE(b) do { *(bf16x8*)(V_lds + (b) * SHM_V + vst0) = vs0; *(bf16x8*)(V_lds + (b) * SHM_V + vst1) = vs1; const int kc = sc * 2;  \
;     *(bf16x8*)(K_lds + (b) * SHM_K + KSWZ(sr, kc)) = ks0; *(bf16x8*)(K_lds + (b) * SHM_K + KSWZ(32 + sr, kc)) = ks1; \
;     if constexpr (NR > 0) *(bf16x8*)(Kr_lds + (b) * SHM_KR + krst) = kr; } while (0)
; #define SLOAD() do { vs0 = *(const bf16x8*)(Vh + voff); vs1 = *(const bf16x8*)(Vh + voff + 32u * (unsigned)ldv); \
;     ks0 = *(const bf16x8*)(Kh + voff); ks1 = *(const bf16x8*)(Kh + voff + 32u * (unsigned)ldv); \
;     if constexpr (NR > 0) { kr = *(const bf16x8*)(Krh + kroff); kroff += 64u * 64u; } voff += 64u * (unsigned)ldv; } while (0)
; __device__ __forceinline__ v8i32 cat8(v4i32 a, v4i32 b) { return (v8i32){a[0], a[1], a[2], a[3], b[0], b[1], b[2], b[3]}; }
; __device__ __forceinline__ void attn_unit7(const unsigned char* __restrict__ Q8, int ldq, const unsigned char* __restrict__ Kn8, int ldk, const unsigned char* __restrict__ Kr8, ...
;     ...
;   float m_reg = 0.f, l_reg = 0; f32x16 o[4] = {}; v8i32 qf[3];
;   { const unsigned char* Qw = Q8 + (unsigned)((wid * 32 + r32) * ldq + hi * 32);
; #pragma unroll
;     for (int s = 0; s < 3; ++s) qf[s] = cat8(*reinterpret_cast<const v4i32*>(Qw + s * 64), *reinterpret_cast<const v4i32*>(Qw + s * 64 + 16)); }
;   const int vtr = tid >> 2, vtc = tid & 3, vtst = vtr * 64 + ((vtc ^ ((vtr >> 2) & 3)) << 4);
;   const int knr = tid >> 3, knc = tid & 7, knst = KN8SW(knr, knc);
;   const int krr = (tid >> 2) & 63, krc = tid & 3, krst = KR8SW(krr, krc);
;   const bool krw = tid < 256;
;   unsigned vtoff = (unsigned)(tid * 16), knoff = (unsigned)(knr * ldk + knc * 16), kroff = (unsigned)(krr * 64 + krc * 16);
;   v4i32 vt, kn, kr;
;     ...
;   f32x16 pA0, pA1, pB0, pB1; float alA, alB; v8i32 p8;
;   SLOAD(); SWRITE(0); __syncthreads();
;   SLOAD();
;   qkt9(pA0, pA1, Kn_lds, Kr_lds, qf, 7.0f - m_reg, r32, hi); partialSM9(pA0, pA1, m_reg, alA, thr_raw);
.LBB0_1320:
	s_or_b64 exec, exec, s[20:21]
	v_and_b32_e32 v0, 0x3fffffc0, v12
	s_mov_b32 s20, 0x60000
	v_lshl_add_u32 v187, v0, 2, 0
	v_add3_u32 v178, v13, v14, s20
	v_add_u32_e32 v0, v15, v16
	v_mov_b32_e32 v14, v1
	v_mov_b32_e32 v15, v1
	v_and_b32_e32 v184, 63, v12
	v_lshl_add_u64 v[180:181], s[12:13], 0, v[0:1]
	v_mov_b32_e32 v0, v1
	v_mov_b32_e32 v2, v1
	v_mov_b32_e32 v3, v1
	v_mov_b32_e32 v4, v1
	v_mov_b32_e32 v5, v1
	v_mov_b32_e32 v6, v1
	v_mov_b32_e32 v7, v1
	v_mov_b32_e32 v8, v1
	v_mov_b32_e32 v9, v1
	v_mov_b32_e32 v10, v1
	v_mov_b32_e32 v11, v1
	v_mov_b32_e32 v12, v1
	v_mov_b32_e32 v13, v1
	v_mov_b64_e32 v[64:65], v[14:15]
	v_mov_b64_e32 v[48:49], v[14:15]
	v_mov_b64_e32 v[32:33], v[14:15]
	v_mov_b64_e32 v[62:63], v[12:13]
	v_mov_b64_e32 v[60:61], v[10:11]
	v_mov_b64_e32 v[58:59], v[8:9]
	v_mov_b64_e32 v[56:57], v[6:7]
	v_mov_b64_e32 v[54:55], v[4:5]
	v_mov_b64_e32 v[52:53], v[2:3]
	v_mov_b64_e32 v[50:51], v[0:1]
	v_mov_b64_e32 v[46:47], v[12:13]
	v_mov_b64_e32 v[44:45], v[10:11]
	v_mov_b64_e32 v[42:43], v[8:9]
	v_mov_b64_e32 v[40:41], v[6:7]
	v_mov_b64_e32 v[38:39], v[4:5]
	v_mov_b64_e32 v[36:37], v[2:3]
	v_mov_b64_e32 v[34:35], v[0:1]
	v_mov_b64_e32 v[30:31], v[12:13]
	v_mov_b64_e32 v[28:29], v[10:11]
	v_mov_b64_e32 v[26:27], v[8:9]
	v_mov_b64_e32 v[24:25], v[6:7]
	v_mov_b64_e32 v[22:23], v[4:5]
	v_mov_b64_e32 v[20:21], v[2:3]
	v_mov_b64_e32 v[18:19], v[0:1]
	v_mov_b64_e32 v[16:17], v[14:15]
	s_lshl_b32 s29, s29, 8
	v_cmp_gt_u32_e64 s[40:41], 32, v184
	v_lshl_add_u32 v208, v183, 2, v187
	v_lshlrev_b32_e32 v207, 4, v175
	v_add_u32_e32 v176, 0x6000, v174
	v_mov_b32_e32 v209, 0
	s_mov_b32 s30, -1
	v_mov_b64_e32 v[14:15], v[12:13]
	v_mov_b64_e32 v[12:13], v[10:11]
	v_mov_b64_e32 v[10:11], v[8:9]
	v_mov_b64_e32 v[8:9], v[6:7]
	v_mov_b64_e32 v[6:7], v[4:5]
	v_mov_b64_e32 v[4:5], v[2:3]
	v_mov_b64_e32 v[2:3], v[0:1]
	v_add_u32_e32 v176, 0xffffe000, v176
	v_add_u32_e32 v178, 0xfffe0000, v178
	v_sub_f32_e32 v230, 0x40e00000, v217
	v_mov_b32_e32 v231, v230
	v_mov_b32_e32 v232, v230
	v_mov_b32_e32 v233, v230
	v_mov_b32_e32 v234, v230
	v_mov_b32_e32 v235, v230
	v_mov_b32_e32 v236, v230
	v_mov_b32_e32 v237, v230
	v_mov_b32_e32 v238, v230
	v_mov_b32_e32 v239, v230
	v_mov_b32_e32 v240, v230
	v_mov_b32_e32 v241, v230
	v_mov_b32_e32 v242, v230
	v_mov_b32_e32 v243, v230
	v_mov_b32_e32 v244, v230
	v_mov_b32_e32 v245, v230
	s_mov_b32 s30, 0
	s_waitcnt lgkmcnt(0)
	s_barrier

; __device__ __forceinline__ void pv8(f32x16* o, const char* Vt, const v8i32 p8, int r32, int hi) {
;   const int sw = (r32 >> 2) & 3, a0 = r32 * 64 + (((hi * 2) ^ sw) << 4), a1 = r32 * 64 + (((hi * 2 + 1) ^ sw) << 4);
; #pragma unroll
;   for (int d0 = 0; d0 < 4; ++d0) {
;     const v8i32 vf = cat8(*reinterpret_cast<const v4i32*>(Vt + d0 * 2048 + a0), *reinterpret_cast<const v4i32*>(Vt + d0 * 2048 + a1));
;     o[d0] = __builtin_amdgcn_mfma_scale_f32_32x32x64_f8f6f4(p8, vf, o[d0], 0, 0, 0, 127, 0, 127); }
; }
; __device__ __forceinline__ void qkt9(f32x16& p0, f32x16& p1, const char* Kn, const char* Kr, const v8i32* qf, const float init, int r32, int hi) {
; #pragma unroll
;   for (int r = 0; r < 16; ++r) { p0[r] = init; p1[r] = init; }
; #pragma unroll
;   for (int s = 0; s < 2; ++s) { const int c0 = s * 4 + hi * 2;
;     const v8i32 a0 = cat8(*reinterpret_cast<const v4i32*>(Kn + KN8SW(r32, c0)), *reinterpret_cast<const v4i32*>(Kn + KN8SW(r32, c0 + 1)));
;     const v8i32 a1 = cat8(*reinterpret_cast<const v4i32*>(Kn + 4096 + KN8SW(r32, c0)), *reinterpret_cast<const v4i32*>(Kn + 4096 + KN8SW(r32, c0 + 1)));
;     p0 = __builtin_amdgcn_mfma_scale_f32_32x32x64_f8f6f4(a0, qf[s], p0, 0, 0, 0, 127, 0, 124);
;     p1 = __builtin_amdgcn_mfma_scale_f32_32x32x64_f8f6f4(a1, qf[s], p1, 0, 0, 0, 127, 0, 124); }
;   { const int c0 = hi * 2;
;     const v8i32 a0 = cat8(*reinterpret_cast<const v4i32*>(Kr + KR8SW(r32, c0)), *reinterpret_cast<const v4i32*>(Kr + KR8SW(r32, c0 + 1)));
; __device__ __forceinline__ void attn_unit7(const unsigned char* __restrict__ Q8, int ldq, const unsigned char* __restrict__ Kn8, int ldk, const unsigned char* __restrict__ Kr8, ...
;     ...
;   for (int j = 1; j + 1 < NT; j += 2) {
;     SLOAD();
;     qkt9(pB0, pB1, Kn_lds + 8192, Kr_lds + 4096, qf, 7.0f - m_reg, r32, hi);
;     finishSM9(pA0, pA1, alA, l_reg, p8);
;     pv8(o, Vt_lds, p8, r32, hi); partialSM9(pB0, pB1, m_reg, alB, thr_raw);
;     __syncthreads(); SWRITE(0);
;     RESC(alB); __syncthreads();
;     if (j + 2 < NT) SLOAD();
;     qkt9(pA0, pA1, Kn_lds, Kr_lds, qf, 7.0f - m_reg, r32, hi);
;     finishSM9(pB0, pB1, alB, l_reg, p8);
;     pv8(o, Vt_lds + 8192, p8, r32, hi); partialSM9(pA0, pA1, m_reg, alA, thr_raw);
;     __syncthreads(); if (j + 2 < NT) SWRITE(1);
;     RESC(alA); __syncthreads();
.Lmla_h0_nokr:
	s_or_b64 exec, exec, s[20:21]
	ds_read_b128 v[114:117], v215 offset:24576
	ds_read_b128 v[118:121], v216 offset:24576
	ds_read_b128 v[222:225], v215 offset:28672
	ds_read_b128 v[226:229], v216 offset:28672
	v_add_u32_e32 v176, 0x2000, v176
	v_add_u32_e32 v178, 0x20000, v178
	s_mov_b64 s[20:21], 0x1000
	v_lshl_add_u64 v[180:181], v[180:181], 0, s[20:21]
	v_exp_f32_e32 v0, v82
	v_exp_f32_e32 v177, v83
	v_exp_f32_e32 v179, v84
	v_exp_f32_e32 v254, v85
	v_add_f32_e32 v219, v0, v177
	v_cvt_pk_fp8_f32 v246, v0, v177
	v_add_f32_e32 v219, v179, v219
	v_add_f32_e32 v219, v254, v219
	v_cvt_pk_fp8_f32 v246, v179, v254 op_sel:[0,0,1]
	s_waitcnt lgkmcnt(2)
	v_mfma_scale_f32_32x32x64_f8f6f4 v[114:129], v[114:121], v[146:153], v[230:245], v194, v193 op_sel_hi:[0,0,0]
	v_exp_f32_e32 v0, v86
	v_exp_f32_e32 v177, v87
	v_exp_f32_e32 v179, v88
	v_exp_f32_e32 v254, v89
	v_add_f32_e32 v219, v0, v219
	v_add_f32_e32 v219, v177, v219
	v_cvt_pk_fp8_f32 v247, v0, v177
	v_add_f32_e32 v219, v179, v219
	v_add_f32_e32 v219, v254, v219
	v_cvt_pk_fp8_f32 v247, v179, v254 op_sel:[0,0,1]
	ds_read_b128 v[82:85], v213 offset:24576
	ds_read_b128 v[86:89], v214 offset:24576
	s_waitcnt lgkmcnt(2)
	v_mfma_scale_f32_32x32x64_f8f6f4 v[98:113], v[222:229], v[146:153], v[230:245], v194, v193 op_sel_hi:[0,0,0]
	ds_read_b128 v[222:225], v213 offset:28672
	ds_read_b128 v[226:229], v214 offset:28672
	v_exp_f32_e32 v0, v90
	v_exp_f32_e32 v177, v91
	v_exp_f32_e32 v179, v92
	v_exp_f32_e32 v254, v93
	v_add_f32_e32 v219, v0, v219
	v_add_f32_e32 v219, v177, v219
	v_cvt_pk_fp8_f32 v248, v0, v177
	v_add_f32_e32 v219, v179, v219
	v_add_f32_e32 v219, v254, v219
	v_cvt_pk_fp8_f32 v248, v179, v254 op_sel:[0,0,1]
	v_exp_f32_e32 v0, v94
	v_exp_f32_e32 v177, v95
	v_exp_f32_e32 v179, v96
	v_exp_f32_e32 v254, v97
	v_add_f32_e32 v219, v0, v219
	v_add_f32_e32 v219, v177, v219
	v_cvt_pk_fp8_f32 v249, v0, v177
	v_add_f32_e32 v219, v179, v219
	v_add_f32_e32 v219, v254, v219
	v_cvt_pk_fp8_f32 v249, v179, v254 op_sel:[0,0,1]
	ds_read_b128 v[90:93], v185 offset:36864
	ds_read_b128 v[94:97], v186 offset:36864
	s_waitcnt lgkmcnt(4)
	v_mfma_scale_f32_32x32x64_f8f6f4 v[114:129], v[82:89], v[138:145], v[114:129], v194, v193 op_sel_hi:[0,0,0]
	v_exp_f32_e32 v0, v66
	v_exp_f32_e32 v177, v67
	v_exp_f32_e32 v179, v68
	v_exp_f32_e32 v254, v69
	v_add_f32_e32 v219, v0, v219
	v_add_f32_e32 v219, v177, v219
	v_cvt_pk_fp8_f32 v250, v0, v177
	v_add_f32_e32 v219, v179, v219
	v_add_f32_e32 v219, v254, v219
	v_cvt_pk_fp8_f32 v250, v179, v254 op_sel:[0,0,1]
	s_waitcnt lgkmcnt(2)
	v_mfma_scale_f32_32x32x64_f8f6f4 v[98:113], v[222:229], v[138:145], v[98:113], v194, v193 op_sel_hi:[0,0,0]
	ds_read_b128 v[222:225], v185 offset:38912
	ds_read_b128 v[226:229], v186 offset:38912
	v_exp_f32_e32 v0, v70
	v_exp_f32_e32 v177, v71
	v_exp_f32_e32 v179, v72
	v_exp_f32_e32 v254, v73
	v_add_f32_e32 v219, v0, v219
	v_add_f32_e32 v219, v177, v219
	v_cvt_pk_fp8_f32 v251, v0, v177
	v_add_f32_e32 v219, v179, v219
	v_add_f32_e32 v219, v254, v219
	v_cvt_pk_fp8_f32 v251, v179, v254 op_sel:[0,0,1]
	v_exp_f32_e32 v0, v74
	v_exp_f32_e32 v177, v75
	v_exp_f32_e32 v179, v76
	v_exp_f32_e32 v254, v77
	v_add_f32_e32 v219, v0, v219
	v_add_f32_e32 v219, v177, v219
	v_cvt_pk_fp8_f32 v252, v0, v177
	v_add_f32_e32 v219, v179, v219
	v_add_f32_e32 v219, v254, v219
	v_cvt_pk_fp8_f32 v252, v179, v254 op_sel:[0,0,1]
	s_waitcnt lgkmcnt(2)
	v_mfma_scale_f32_32x32x64_f8f6f4 v[114:129], v[90:97], v[130:137], v[114:129], v194, v193 op_sel_hi:[0,0,0]
	v_exp_f32_e32 v0, v78
	v_exp_f32_e32 v177, v79
	v_exp_f32_e32 v179, v80
	v_exp_f32_e32 v254, v81
	v_add_f32_e32 v219, v0, v219
	v_add_f32_e32 v219, v177, v219
	v_cvt_pk_fp8_f32 v253, v0, v177
	v_add_f32_e32 v219, v179, v219
	v_add_f32_e32 v219, v254, v219
	v_cvt_pk_fp8_f32 v253, v179, v254 op_sel:[0,0,1]
	ds_read_b128 v[90:93], v185 offset:0
	ds_read_b128 v[94:97], v186 offset:0
	ds_read_b128 v[82:85], v185 offset:2048
	ds_read_b128 v[86:89], v186 offset:2048
	ds_read_b128 v[74:77], v185 offset:4096
	ds_read_b128 v[78:81], v186 offset:4096
	ds_read_b128 v[66:69], v185 offset:6144
	ds_read_b128 v[70:73], v186 offset:6144
	s_waitcnt lgkmcnt(8)
	v_mfma_scale_f32_32x32x64_f8f6f4 v[98:113], v[222:229], v[130:137], v[98:113], v194, v193 op_sel_hi:[0,0,0]
	v_mov_b32_e32 v0, v219
	s_nop 1
	v_permlane32_swap_b32_e32 v219, v0
	v_add_f32_e32 v219, v219, v0
	v_fma_f32 v209, v209, v218, v219
	v_max_f32_e32 v177, v114, v115
	v_max3_f32 v177, v177, v116, v117
	v_max3_f32 v177, v177, v118, v119
	v_max3_f32 v177, v177, v120, v121
	v_max3_f32 v177, v177, v122, v123
	v_max3_f32 v177, v177, v124, v125
	v_max3_f32 v177, v177, v126, v127
	v_max3_f32 v177, v177, v128, v129
	s_waitcnt lgkmcnt(6)
	v_mfma_scale_f32_32x32x64_f8f6f4 v[50:65], v[246:253], v[90:97], v[50:65], v194, v194 op_sel_hi:[0,0,0]
	s_waitcnt lgkmcnt(4)
	v_mfma_scale_f32_32x32x64_f8f6f4 v[34:49], v[246:253], v[82:89], v[34:49], v194, v194 op_sel_hi:[0,0,0]
	s_waitcnt lgkmcnt(2)
	v_mfma_scale_f32_32x32x64_f8f6f4 v[18:33], v[246:253], v[74:81], v[18:33], v194, v194 op_sel_hi:[0,0,0]
	s_waitcnt lgkmcnt(0)
	v_mfma_scale_f32_32x32x64_f8f6f4 v[2:17], v[246:253], v[66:73], v[2:17], v194, v194 op_sel_hi:[0,0,0]
	s_waitcnt vmcnt(0)
	ds_write_b128 v210, v[158:161] offset:43008
	ds_write_b128 v211, v[162:165] offset:51200
	s_and_saveexec_b64 s[20:21], s[42:43]
	ds_write_b128 v212, v[154:157] offset:59392
	s_or_b64 exec, exec, s[20:21]
	v_max_f32_e32 v0, v98, v99
	v_max3_f32 v0, v0, v100, v101
	v_max3_f32 v0, v0, v102, v103
	v_max3_f32 v0, v0, v104, v105
	v_max3_f32 v0, v0, v106, v107
	v_max3_f32 v0, v0, v108, v109
	v_max3_f32 v0, v0, v110, v111
	v_max3_f32 v0, v0, v112, v113
	v_max_f32_e32 v177, v177, v0
	v_mov_b32_e32 v0, v177
	v_mov_b32_e32 v221, 1.0
	s_nop 0
	v_permlane32_swap_b32_e32 v177, v0
	v_max_f32_e32 v177, v177, v0
	v_cmp_ge_f32_e32 vcc, s90, v177
	s_cmp_eq_u64 vcc, exec
	s_cbranch_scc0 .Lmla_h0_newmax

; __device__ __forceinline__ void pv8(f32x16* o, const char* Vt, const v8i32 p8, int r32, int hi) {
;   const int sw = (r32 >> 2) & 3, a0 = r32 * 64 + (((hi * 2) ^ sw) << 4), a1 = r32 * 64 + (((hi * 2 + 1) ^ sw) << 4);
; #pragma unroll
;   for (int d0 = 0; d0 < 4; ++d0) {
;     const v8i32 vf = cat8(*reinterpret_cast<const v4i32*>(Vt + d0 * 2048 + a0), *reinterpret_cast<const v4i32*>(Vt + d0 * 2048 + a1));
;     o[d0] = __builtin_amdgcn_mfma_scale_f32_32x32x64_f8f6f4(p8, vf, o[d0], 0, 0, 0, 127, 0, 127); }
; }
; __device__ __forceinline__ void qkt9(f32x16& p0, f32x16& p1, const char* Kn, const char* Kr, const v8i32* qf, const float init, int r32, int hi) {
; #pragma unroll
;   for (int r = 0; r < 16; ++r) { p0[r] = init; p1[r] = init; }
; #pragma unroll
;   for (int s = 0; s < 2; ++s) { const int c0 = s * 4 + hi * 2;
;     const v8i32 a0 = cat8(*reinterpret_cast<const v4i32*>(Kn + KN8SW(r32, c0)), *reinterpret_cast<const v4i32*>(Kn + KN8SW(r32, c0 + 1)));
;     const v8i32 a1 = cat8(*reinterpret_cast<const v4i32*>(Kn + 4096 + KN8SW(r32, c0)), *reinterpret_cast<const v4i32*>(Kn + 4096 + KN8SW(r32, c0 + 1)));
;     p0 = __builtin_amdgcn_mfma_scale_f32_32x32x64_f8f6f4(a0, qf[s], p0, 0, 0, 0, 127, 0, 124);
;     p1 = __builtin_amdgcn_mfma_scale_f32_32x32x64_f8f6f4(a1, qf[s], p1, 0, 0, 0, 127, 0, 124); }
;   { const int c0 = hi * 2;
;     const v8i32 a0 = cat8(*reinterpret_cast<const v4i32*>(Kr + KR8SW(r32, c0)), *reinterpret_cast<const v4i32*>(Kr + KR8SW(r32, c0 + 1)));
; __device__ __forceinline__ void attn_unit7(const unsigned char* __restrict__ Q8, int ldq, const unsigned char* __restrict__ Kn8, int ldk, const unsigned char* __restrict__ Kr8, ...
;     ...
;   for (int j = 1; j + 1 < NT; j += 2) {
;     SLOAD();
;     qkt9(pB0, pB1, Kn_lds + 8192, Kr_lds + 4096, qf, 7.0f - m_reg, r32, hi);
;     finishSM9(pA0, pA1, alA, l_reg, p8);
;     pv8(o, Vt_lds, p8, r32, hi); partialSM9(pB0, pB1, m_reg, alB, thr_raw);
;     __syncthreads(); SWRITE(0);
;     RESC(alB); __syncthreads();
;     if (j + 2 < NT) SLOAD();
;     qkt9(pA0, pA1, Kn_lds, Kr_lds, qf, 7.0f - m_reg, r32, hi);
;     finishSM9(pB0, pB1, alB, l_reg, p8);
;     pv8(o, Vt_lds + 8192, p8, r32, hi); partialSM9(pA0, pA1, m_reg, alA, thr_raw);
;     __syncthreads(); if (j + 2 < NT) SWRITE(1);
;     RESC(alA); __syncthreads();
.Lmla_h1_nokr:
	s_or_b64 exec, exec, s[20:21]
	ds_read_b128 v[82:85], v215 offset:51200
	ds_read_b128 v[86:89], v216 offset:51200
	ds_read_b128 v[222:225], v215 offset:55296
	ds_read_b128 v[226:229], v216 offset:55296
	v_add_u32_e32 v176, 0x2000, v176
	v_add_u32_e32 v178, 0x20000, v178
	s_mov_b64 s[20:21], 0x1000
	v_lshl_add_u64 v[180:181], v[180:181], 0, s[20:21]
	v_exp_f32_e32 v0, v114
	v_exp_f32_e32 v177, v115
	v_exp_f32_e32 v179, v116
	v_exp_f32_e32 v254, v117
	v_add_f32_e32 v219, v0, v177
	v_cvt_pk_fp8_f32 v246, v0, v177
	v_add_f32_e32 v219, v179, v219
	v_add_f32_e32 v219, v254, v219
	v_cvt_pk_fp8_f32 v246, v179, v254 op_sel:[0,0,1]
	s_waitcnt lgkmcnt(2)
	v_mfma_scale_f32_32x32x64_f8f6f4 v[82:97], v[82:89], v[146:153], v[230:245], v194, v193 op_sel_hi:[0,0,0]
	v_exp_f32_e32 v0, v118
	v_exp_f32_e32 v177, v119
	v_exp_f32_e32 v179, v120
	v_exp_f32_e32 v254, v121
	v_add_f32_e32 v219, v0, v219
	v_add_f32_e32 v219, v177, v219
	v_cvt_pk_fp8_f32 v247, v0, v177
	v_add_f32_e32 v219, v179, v219
	v_add_f32_e32 v219, v254, v219
	v_cvt_pk_fp8_f32 v247, v179, v254 op_sel:[0,0,1]
	ds_read_b128 v[114:117], v213 offset:51200
	ds_read_b128 v[118:121], v214 offset:51200
	s_waitcnt lgkmcnt(2)
	v_mfma_scale_f32_32x32x64_f8f6f4 v[66:81], v[222:229], v[146:153], v[230:245], v194, v193 op_sel_hi:[0,0,0]
	ds_read_b128 v[222:225], v213 offset:55296
	ds_read_b128 v[226:229], v214 offset:55296
	v_exp_f32_e32 v0, v122
	v_exp_f32_e32 v177, v123
	v_exp_f32_e32 v179, v124
	v_exp_f32_e32 v254, v125
	v_add_f32_e32 v219, v0, v219
	v_add_f32_e32 v219, v177, v219
	v_cvt_pk_fp8_f32 v248, v0, v177
	v_add_f32_e32 v219, v179, v219
	v_add_f32_e32 v219, v254, v219
	v_cvt_pk_fp8_f32 v248, v179, v254 op_sel:[0,0,1]
	v_exp_f32_e32 v0, v126
	v_exp_f32_e32 v177, v127
	v_exp_f32_e32 v179, v128
	v_exp_f32_e32 v254, v129
	v_add_f32_e32 v219, v0, v219
	v_add_f32_e32 v219, v177, v219
	v_cvt_pk_fp8_f32 v249, v0, v177
	v_add_f32_e32 v219, v179, v219
	v_add_f32_e32 v219, v254, v219
	v_cvt_pk_fp8_f32 v249, v179, v254 op_sel:[0,0,1]
	ds_read_b128 v[122:125], v185 offset:59392
	ds_read_b128 v[126:129], v186 offset:59392
	s_waitcnt lgkmcnt(4)
	v_mfma_scale_f32_32x32x64_f8f6f4 v[82:97], v[114:121], v[138:145], v[82:97], v194, v193 op_sel_hi:[0,0,0]
	v_exp_f32_e32 v0, v98
	v_exp_f32_e32 v177, v99
	v_exp_f32_e32 v179, v100
	v_exp_f32_e32 v254, v101
	v_add_f32_e32 v219, v0, v219
	v_add_f32_e32 v219, v177, v219
	v_cvt_pk_fp8_f32 v250, v0, v177
	v_add_f32_e32 v219, v179, v219
	v_add_f32_e32 v219, v254, v219
	v_cvt_pk_fp8_f32 v250, v179, v254 op_sel:[0,0,1]
	s_waitcnt lgkmcnt(2)
	v_mfma_scale_f32_32x32x64_f8f6f4 v[66:81], v[222:229], v[138:145], v[66:81], v194, v193 op_sel_hi:[0,0,0]
	ds_read_b128 v[222:225], v185 offset:61440
	ds_read_b128 v[226:229], v186 offset:61440
	v_exp_f32_e32 v0, v102
	v_exp_f32_e32 v177, v103
	v_exp_f32_e32 v179, v104
	v_exp_f32_e32 v254, v105
	v_add_f32_e32 v219, v0, v219
	v_add_f32_e32 v219, v177, v219
	v_cvt_pk_fp8_f32 v251, v0, v177
	v_add_f32_e32 v219, v179, v219
	v_add_f32_e32 v219, v254, v219
	v_cvt_pk_fp8_f32 v251, v179, v254 op_sel:[0,0,1]
	v_exp_f32_e32 v0, v106
	v_exp_f32_e32 v177, v107
	v_exp_f32_e32 v179, v108
	v_exp_f32_e32 v254, v109
	v_add_f32_e32 v219, v0, v219
	v_add_f32_e32 v219, v177, v219
	v_cvt_pk_fp8_f32 v252, v0, v177
	v_add_f32_e32 v219, v179, v219
	v_add_f32_e32 v219, v254, v219
	v_cvt_pk_fp8_f32 v252, v179, v254 op_sel:[0,0,1]
	s_waitcnt lgkmcnt(2)
	v_mfma_scale_f32_32x32x64_f8f6f4 v[82:97], v[122:129], v[130:137], v[82:97], v194, v193 op_sel_hi:[0,0,0]
	v_exp_f32_e32 v0, v110
	v_exp_f32_e32 v177, v111
	v_exp_f32_e32 v179, v112
	v_exp_f32_e32 v254, v113
	v_add_f32_e32 v219, v0, v219
	v_add_f32_e32 v219, v177, v219
	v_cvt_pk_fp8_f32 v253, v0, v177
	v_add_f32_e32 v219, v179, v219
	v_add_f32_e32 v219, v254, v219
	v_cvt_pk_fp8_f32 v253, v179, v254 op_sel:[0,0,1]
	ds_read_b128 v[122:125], v185 offset:8192
	ds_read_b128 v[126:129], v186 offset:8192
	ds_read_b128 v[114:117], v185 offset:10240
	ds_read_b128 v[118:121], v186 offset:10240
	ds_read_b128 v[106:109], v185 offset:12288
	ds_read_b128 v[110:113], v186 offset:12288
	ds_read_b128 v[98:101], v185 offset:14336
	ds_read_b128 v[102:105], v186 offset:14336
	s_waitcnt lgkmcnt(8)
	v_mfma_scale_f32_32x32x64_f8f6f4 v[66:81], v[222:229], v[130:137], v[66:81], v194, v193 op_sel_hi:[0,0,0]
	v_mov_b32_e32 v0, v219
	s_nop 1
	v_permlane32_swap_b32_e32 v219, v0
	v_add_f32_e32 v219, v219, v0
	v_fma_f32 v209, v209, v221, v219
	v_max_f32_e32 v177, v82, v83
	v_max3_f32 v177, v177, v84, v85
	v_max3_f32 v177, v177, v86, v87
	v_max3_f32 v177, v177, v88, v89
	v_max3_f32 v177, v177, v90, v91
	v_max3_f32 v177, v177, v92, v93
	v_max3_f32 v177, v177, v94, v95
	v_max3_f32 v177, v177, v96, v97
	s_waitcnt lgkmcnt(6)
	v_mfma_scale_f32_32x32x64_f8f6f4 v[50:65], v[246:253], v[122:129], v[50:65], v194, v194 op_sel_hi:[0,0,0]
	s_waitcnt lgkmcnt(4)
	v_mfma_scale_f32_32x32x64_f8f6f4 v[34:49], v[246:253], v[114:121], v[34:49], v194, v194 op_sel_hi:[0,0,0]
	s_waitcnt lgkmcnt(2)
	v_mfma_scale_f32_32x32x64_f8f6f4 v[18:33], v[246:253], v[106:113], v[18:33], v194, v194 op_sel_hi:[0,0,0]
	s_waitcnt lgkmcnt(0)
	v_mfma_scale_f32_32x32x64_f8f6f4 v[2:17], v[246:253], v[98:105], v[2:17], v194, v194 op_sel_hi:[0,0,0]
	s_waitcnt vmcnt(0)
	ds_write_b128 v210, v[158:161]
	ds_write_b128 v211, v[162:165] offset:16384
	s_and_saveexec_b64 s[20:21], s[42:43]
	ds_write_b128 v212, v[154:157] offset:32768
	s_or_b64 exec, exec, s[20:21]
	v_max_f32_e32 v0, v66, v67
	v_max3_f32 v0, v0, v68, v69
	v_max3_f32 v0, v0, v70, v71
	v_max3_f32 v0, v0, v72, v73
	v_max3_f32 v0, v0, v74, v75
	v_max3_f32 v0, v0, v76, v77
	v_max3_f32 v0, v0, v78, v79
	v_max3_f32 v0, v0, v80, v81
	v_max_f32_e32 v177, v177, v0
	v_mov_b32_e32 v0, v177
	v_mov_b32_e32 v218, 1.0
	s_nop 0
	v_permlane32_swap_b32_e32 v177, v0
	v_max_f32_e32 v177, v177, v0
	v_cmp_ge_f32_e32 vcc, s90, v177
	s_cmp_eq_u64 vcc, exec
	s_cbranch_scc0 .Lmla_h1_newmax

; __device__ __forceinline__ void pv8(f32x16* o, const char* Vt, const v8i32 p8, int r32, int hi) {
;   const int sw = (r32 >> 2) & 3, a0 = r32 * 64 + (((hi * 2) ^ sw) << 4), a1 = r32 * 64 + (((hi * 2 + 1) ^ sw) << 4);
; #pragma unroll
;   for (int d0 = 0; d0 < 4; ++d0) {
;     const v8i32 vf = cat8(*reinterpret_cast<const v4i32*>(Vt + d0 * 2048 + a0), *reinterpret_cast<const v4i32*>(Vt + d0 * 2048 + a1));
;     o[d0] = __builtin_amdgcn_mfma_scale_f32_32x32x64_f8f6f4(p8, vf, o[d0], 0, 0, 0, 127, 0, 127); }
; }
; __device__ __forceinline__ void qkt9(f32x16& p0, f32x16& p1, const char* Kn, const char* Kr, const v8i32* qf, const float init, int r32, int hi) {
; #pragma unroll
;   for (int r = 0; r < 16; ++r) { p0[r] = init; p1[r] = init; }
; #pragma unroll
;   for (int s = 0; s < 2; ++s) { const int c0 = s * 4 + hi * 2;
;     const v8i32 a0 = cat8(*reinterpret_cast<const v4i32*>(Kn + KN8SW(r32, c0)), *reinterpret_cast<const v4i32*>(Kn + KN8SW(r32, c0 + 1)));
;     const v8i32 a1 = cat8(*reinterpret_cast<const v4i32*>(Kn + 4096 + KN8SW(r32, c0)), *reinterpret_cast<const v4i32*>(Kn + 4096 + KN8SW(r32, c0 + 1)));
;     p0 = __builtin_amdgcn_mfma_scale_f32_32x32x64_f8f6f4(a0, qf[s], p0, 0, 0, 0, 127, 0, 124);
;     p1 = __builtin_amdgcn_mfma_scale_f32_32x32x64_f8f6f4(a1, qf[s], p1, 0, 0, 0, 127, 0, 124); }
;   { const int c0 = hi * 2;
;     const v8i32 a0 = cat8(*reinterpret_cast<const v4i32*>(Kr + KR8SW(r32, c0)), *reinterpret_cast<const v4i32*>(Kr + KR8SW(r32, c0 + 1)));
; __device__ __forceinline__ void attn_unit7(const unsigned char* __restrict__ Q8, int ldq, const unsigned char* __restrict__ Kn8, int ldk, const unsigned char* __restrict__ Kr8, ...
;     ...
;   for (int j = 1; j + 1 < NT; j += 2) {
;     SLOAD();
;     qkt9(pB0, pB1, Kn_lds + 8192, Kr_lds + 4096, qf, 7.0f - m_reg, r32, hi);
;     finishSM9(pA0, pA1, alA, l_reg, p8);
;     pv8(o, Vt_lds, p8, r32, hi); partialSM9(pB0, pB1, m_reg, alB, thr_raw);
;     __syncthreads(); SWRITE(0);
;     RESC(alB); __syncthreads();
;     if (j + 2 < NT) SLOAD();
;     qkt9(pA0, pA1, Kn_lds, Kr_lds, qf, 7.0f - m_reg, r32, hi);
;     finishSM9(pB0, pB1, alB, l_reg, p8);
;     pv8(o, Vt_lds + 8192, p8, r32, hi); partialSM9(pA0, pA1, m_reg, alA, thr_raw);
;     __syncthreads(); if (j + 2 < NT) SWRITE(1);
;     RESC(alA); __syncthreads();
.Lmla_h2_nokr:
	s_or_b64 exec, exec, s[20:21]
	ds_read_b128 v[114:117], v215 offset:16384
	ds_read_b128 v[118:121], v216 offset:16384
	ds_read_b128 v[222:225], v215 offset:20480
	ds_read_b128 v[226:229], v216 offset:20480
	v_add_u32_e32 v176, 0x2000, v176
	v_add_u32_e32 v178, 0x20000, v178
	s_mov_b64 s[20:21], 0x1000
	v_lshl_add_u64 v[180:181], v[180:181], 0, s[20:21]
	v_exp_f32_e32 v0, v82
	v_exp_f32_e32 v177, v83
	v_exp_f32_e32 v179, v84
	v_exp_f32_e32 v254, v85
	v_add_f32_e32 v219, v0, v177
	v_cvt_pk_fp8_f32 v246, v0, v177
	v_add_f32_e32 v219, v179, v219
	v_add_f32_e32 v219, v254, v219
	v_cvt_pk_fp8_f32 v246, v179, v254 op_sel:[0,0,1]
	s_waitcnt lgkmcnt(2)
	v_mfma_scale_f32_32x32x64_f8f6f4 v[114:129], v[114:121], v[146:153], v[230:245], v194, v193 op_sel_hi:[0,0,0]
	v_exp_f32_e32 v0, v86
	v_exp_f32_e32 v177, v87
	v_exp_f32_e32 v179, v88
	v_exp_f32_e32 v254, v89
	v_add_f32_e32 v219, v0, v219
	v_add_f32_e32 v219, v177, v219
	v_cvt_pk_fp8_f32 v247, v0, v177
	v_add_f32_e32 v219, v179, v219
	v_add_f32_e32 v219, v254, v219
	v_cvt_pk_fp8_f32 v247, v179, v254 op_sel:[0,0,1]
	ds_read_b128 v[82:85], v213 offset:16384
	ds_read_b128 v[86:89], v214 offset:16384
	s_waitcnt lgkmcnt(2)
	v_mfma_scale_f32_32x32x64_f8f6f4 v[98:113], v[222:229], v[146:153], v[230:245], v194, v193 op_sel_hi:[0,0,0]
	ds_read_b128 v[222:225], v213 offset:20480
	ds_read_b128 v[226:229], v214 offset:20480
	v_exp_f32_e32 v0, v90
	v_exp_f32_e32 v177, v91
	v_exp_f32_e32 v179, v92
	v_exp_f32_e32 v254, v93
	v_add_f32_e32 v219, v0, v219
	v_add_f32_e32 v219, v177, v219
	v_cvt_pk_fp8_f32 v248, v0, v177
	v_add_f32_e32 v219, v179, v219
	v_add_f32_e32 v219, v254, v219
	v_cvt_pk_fp8_f32 v248, v179, v254 op_sel:[0,0,1]
	v_exp_f32_e32 v0, v94
	v_exp_f32_e32 v177, v95
	v_exp_f32_e32 v179, v96
	v_exp_f32_e32 v254, v97
	v_add_f32_e32 v219, v0, v219
	v_add_f32_e32 v219, v177, v219
	v_cvt_pk_fp8_f32 v249, v0, v177
	v_add_f32_e32 v219, v179, v219
	v_add_f32_e32 v219, v254, v219
	v_cvt_pk_fp8_f32 v249, v179, v254 op_sel:[0,0,1]
	ds_read_b128 v[90:93], v185 offset:32768
	ds_read_b128 v[94:97], v186 offset:32768
	s_waitcnt lgkmcnt(4)
	v_mfma_scale_f32_32x32x64_f8f6f4 v[114:129], v[82:89], v[138:145], v[114:129], v194, v193 op_sel_hi:[0,0,0]
	v_exp_f32_e32 v0, v66
	v_exp_f32_e32 v177, v67
	v_exp_f32_e32 v179, v68
	v_exp_f32_e32 v254, v69
	v_add_f32_e32 v219, v0, v219
	v_add_f32_e32 v219, v177, v219
	v_cvt_pk_fp8_f32 v250, v0, v177
	v_add_f32_e32 v219, v179, v219
	v_add_f32_e32 v219, v254, v219
	v_cvt_pk_fp8_f32 v250, v179, v254 op_sel:[0,0,1]
	s_waitcnt lgkmcnt(2)
	v_mfma_scale_f32_32x32x64_f8f6f4 v[98:113], v[222:229], v[138:145], v[98:113], v194, v193 op_sel_hi:[0,0,0]
	ds_read_b128 v[222:225], v185 offset:34816
	ds_read_b128 v[226:229], v186 offset:34816
	v_exp_f32_e32 v0, v70
	v_exp_f32_e32 v177, v71
	v_exp_f32_e32 v179, v72
	v_exp_f32_e32 v254, v73
	v_add_f32_e32 v219, v0, v219
	v_add_f32_e32 v219, v177, v219
	v_cvt_pk_fp8_f32 v251, v0, v177
	v_add_f32_e32 v219, v179, v219
	v_add_f32_e32 v219, v254, v219
	v_cvt_pk_fp8_f32 v251, v179, v254 op_sel:[0,0,1]
	v_exp_f32_e32 v0, v74
	v_exp_f32_e32 v177, v75
	v_exp_f32_e32 v179, v76
	v_exp_f32_e32 v254, v77
	v_add_f32_e32 v219, v0, v219
	v_add_f32_e32 v219, v177, v219
	v_cvt_pk_fp8_f32 v252, v0, v177
	v_add_f32_e32 v219, v179, v219
	v_add_f32_e32 v219, v254, v219
	v_cvt_pk_fp8_f32 v252, v179, v254 op_sel:[0,0,1]
	s_waitcnt lgkmcnt(2)
	v_mfma_scale_f32_32x32x64_f8f6f4 v[114:129], v[90:97], v[130:137], v[114:129], v194, v193 op_sel_hi:[0,0,0]
	v_exp_f32_e32 v0, v78
	v_exp_f32_e32 v177, v79
	v_exp_f32_e32 v179, v80
	v_exp_f32_e32 v254, v81
	v_add_f32_e32 v219, v0, v219
	v_add_f32_e32 v219, v177, v219
	v_cvt_pk_fp8_f32 v253, v0, v177
	v_add_f32_e32 v219, v179, v219
	v_add_f32_e32 v219, v254, v219
	v_cvt_pk_fp8_f32 v253, v179, v254 op_sel:[0,0,1]
	ds_read_b128 v[90:93], v185 offset:43008
	ds_read_b128 v[94:97], v186 offset:43008
	ds_read_b128 v[82:85], v185 offset:45056
	ds_read_b128 v[86:89], v186 offset:45056
	ds_read_b128 v[74:77], v185 offset:47104
	ds_read_b128 v[78:81], v186 offset:47104
	ds_read_b128 v[66:69], v185 offset:49152
	ds_read_b128 v[70:73], v186 offset:49152
	s_waitcnt lgkmcnt(8)
	v_mfma_scale_f32_32x32x64_f8f6f4 v[98:113], v[222:229], v[130:137], v[98:113], v194, v193 op_sel_hi:[0,0,0]
	v_mov_b32_e32 v0, v219
	s_nop 1
	v_permlane32_swap_b32_e32 v219, v0
	v_add_f32_e32 v219, v219, v0
	v_fma_f32 v209, v209, v218, v219
	v_max_f32_e32 v177, v114, v115
	v_max3_f32 v177, v177, v116, v117
	v_max3_f32 v177, v177, v118, v119
	v_max3_f32 v177, v177, v120, v121
	v_max3_f32 v177, v177, v122, v123
	v_max3_f32 v177, v177, v124, v125
	v_max3_f32 v177, v177, v126, v127
	v_max3_f32 v177, v177, v128, v129
	s_waitcnt lgkmcnt(6)
	v_mfma_scale_f32_32x32x64_f8f6f4 v[50:65], v[246:253], v[90:97], v[50:65], v194, v194 op_sel_hi:[0,0,0]
	s_waitcnt lgkmcnt(4)
	v_mfma_scale_f32_32x32x64_f8f6f4 v[34:49], v[246:253], v[82:89], v[34:49], v194, v194 op_sel_hi:[0,0,0]
	s_waitcnt lgkmcnt(2)
	v_mfma_scale_f32_32x32x64_f8f6f4 v[18:33], v[246:253], v[74:81], v[18:33], v194, v194 op_sel_hi:[0,0,0]
	s_waitcnt lgkmcnt(0)
	v_mfma_scale_f32_32x32x64_f8f6f4 v[2:17], v[246:253], v[66:73], v[2:17], v194, v194 op_sel_hi:[0,0,0]
	s_waitcnt vmcnt(0)
	ds_write_b128 v210, v[158:161] offset:8192
	ds_write_b128 v211, v[162:165] offset:24576
	s_and_saveexec_b64 s[20:21], s[42:43]
	ds_write_b128 v212, v[154:157] offset:36864
	s_or_b64 exec, exec, s[20:21]
	v_max_f32_e32 v0, v98, v99
	v_max3_f32 v0, v0, v100, v101
	v_max3_f32 v0, v0, v102, v103
	v_max3_f32 v0, v0, v104, v105
	v_max3_f32 v0, v0, v106, v107
	v_max3_f32 v0, v0, v108, v109
	v_max3_f32 v0, v0, v110, v111
	v_max3_f32 v0, v0, v112, v113
	v_max_f32_e32 v177, v177, v0
	v_mov_b32_e32 v0, v177
	v_mov_b32_e32 v221, 1.0
	s_nop 0
	v_permlane32_swap_b32_e32 v177, v0
	v_max_f32_e32 v177, v177, v0
	v_cmp_ge_f32_e32 vcc, s90, v177
	s_cmp_eq_u64 vcc, exec
	s_cbranch_scc0 .Lmla_h2_newmax

; __device__ __forceinline__ void pv8(f32x16* o, const char* Vt, const v8i32 p8, int r32, int hi) {
;   const int sw = (r32 >> 2) & 3, a0 = r32 * 64 + (((hi * 2) ^ sw) << 4), a1 = r32 * 64 + (((hi * 2 + 1) ^ sw) << 4);
; #pragma unroll
;   for (int d0 = 0; d0 < 4; ++d0) {
;     const v8i32 vf = cat8(*reinterpret_cast<const v4i32*>(Vt + d0 * 2048 + a0), *reinterpret_cast<const v4i32*>(Vt + d0 * 2048 + a1));
;     o[d0] = __builtin_amdgcn_mfma_scale_f32_32x32x64_f8f6f4(p8, vf, o[d0], 0, 0, 0, 127, 0, 127); }
; }
; __device__ __forceinline__ void qkt9(f32x16& p0, f32x16& p1, const char* Kn, const char* Kr, const v8i32* qf, const float init, int r32, int hi) {
; #pragma unroll
;   for (int r = 0; r < 16; ++r) { p0[r] = init; p1[r] = init; }
; #pragma unroll
;   for (int s = 0; s < 2; ++s) { const int c0 = s * 4 + hi * 2;
;     const v8i32 a0 = cat8(*reinterpret_cast<const v4i32*>(Kn + KN8SW(r32, c0)), *reinterpret_cast<const v4i32*>(Kn + KN8SW(r32, c0 + 1)));
;     const v8i32 a1 = cat8(*reinterpret_cast<const v4i32*>(Kn + 4096 + KN8SW(r32, c0)), *reinterpret_cast<const v4i32*>(Kn + 4096 + KN8SW(r32, c0 + 1)));
;     p0 = __builtin_amdgcn_mfma_scale_f32_32x32x64_f8f6f4(a0, qf[s], p0, 0, 0, 0, 127, 0, 124);
;     p1 = __builtin_amdgcn_mfma_scale_f32_32x32x64_f8f6f4(a1, qf[s], p1, 0, 0, 0, 127, 0, 124); }
;   { const int c0 = hi * 2;
;     const v8i32 a0 = cat8(*reinterpret_cast<const v4i32*>(Kr + KR8SW(r32, c0)), *reinterpret_cast<const v4i32*>(Kr + KR8SW(r32, c0 + 1)));
; __device__ __forceinline__ void attn_unit7(const unsigned char* __restrict__ Q8, int ldq, const unsigned char* __restrict__ Kn8, int ldk, const unsigned char* __restrict__ Kr8, ...
;     ...
;   for (int j = 1; j + 1 < NT; j += 2) {
;     SLOAD();
;     qkt9(pB0, pB1, Kn_lds + 8192, Kr_lds + 4096, qf, 7.0f - m_reg, r32, hi);
;     finishSM9(pA0, pA1, alA, l_reg, p8);
;     pv8(o, Vt_lds, p8, r32, hi); partialSM9(pB0, pB1, m_reg, alB, thr_raw);
;     __syncthreads(); SWRITE(0);
;     RESC(alB); __syncthreads();
;     if (j + 2 < NT) SLOAD();
;     qkt9(pA0, pA1, Kn_lds, Kr_lds, qf, 7.0f - m_reg, r32, hi);
;     finishSM9(pB0, pB1, alB, l_reg, p8);
;     pv8(o, Vt_lds + 8192, p8, r32, hi); partialSM9(pA0, pA1, m_reg, alA, thr_raw);
;     __syncthreads(); if (j + 2 < NT) SWRITE(1);
;     RESC(alA); __syncthreads();
.Lmla_h3_nokr:
	s_or_b64 exec, exec, s[20:21]
	ds_read_b128 v[82:85], v215 offset:24576
	ds_read_b128 v[86:89], v216 offset:24576
	ds_read_b128 v[222:225], v215 offset:28672
	ds_read_b128 v[226:229], v216 offset:28672
	v_add_u32_e32 v176, 0x2000, v176
	v_add_u32_e32 v178, 0x20000, v178
	s_mov_b64 s[20:21], 0x1000
	v_lshl_add_u64 v[180:181], v[180:181], 0, s[20:21]
	v_exp_f32_e32 v0, v114
	v_exp_f32_e32 v177, v115
	v_exp_f32_e32 v179, v116
	v_exp_f32_e32 v254, v117
	v_add_f32_e32 v219, v0, v177
	v_cvt_pk_fp8_f32 v246, v0, v177
	v_add_f32_e32 v219, v179, v219
	v_add_f32_e32 v219, v254, v219
	v_cvt_pk_fp8_f32 v246, v179, v254 op_sel:[0,0,1]
	s_waitcnt lgkmcnt(2)
	v_mfma_scale_f32_32x32x64_f8f6f4 v[82:97], v[82:89], v[146:153], v[230:245], v194, v193 op_sel_hi:[0,0,0]
	v_exp_f32_e32 v0, v118
	v_exp_f32_e32 v177, v119
	v_exp_f32_e32 v179, v120
	v_exp_f32_e32 v254, v121
	v_add_f32_e32 v219, v0, v219
	v_add_f32_e32 v219, v177, v219
	v_cvt_pk_fp8_f32 v247, v0, v177
	v_add_f32_e32 v219, v179, v219
	v_add_f32_e32 v219, v254, v219
	v_cvt_pk_fp8_f32 v247, v179, v254 op_sel:[0,0,1]
	ds_read_b128 v[114:117], v213 offset:24576
	ds_read_b128 v[118:121], v214 offset:24576
	s_waitcnt lgkmcnt(2)
	v_mfma_scale_f32_32x32x64_f8f6f4 v[66:81], v[222:229], v[146:153], v[230:245], v194, v193 op_sel_hi:[0,0,0]
	ds_read_b128 v[222:225], v213 offset:28672
	ds_read_b128 v[226:229], v214 offset:28672
	v_exp_f32_e32 v0, v122
	v_exp_f32_e32 v177, v123
	v_exp_f32_e32 v179, v124
	v_exp_f32_e32 v254, v125
	v_add_f32_e32 v219, v0, v219
	v_add_f32_e32 v219, v177, v219
	v_cvt_pk_fp8_f32 v248, v0, v177
	v_add_f32_e32 v219, v179, v219
	v_add_f32_e32 v219, v254, v219
	v_cvt_pk_fp8_f32 v248, v179, v254 op_sel:[0,0,1]
	v_exp_f32_e32 v0, v126
	v_exp_f32_e32 v177, v127
	v_exp_f32_e32 v179, v128
	v_exp_f32_e32 v254, v129
	v_add_f32_e32 v219, v0, v219
	v_add_f32_e32 v219, v177, v219
	v_cvt_pk_fp8_f32 v249, v0, v177
	v_add_f32_e32 v219, v179, v219
	v_add_f32_e32 v219, v254, v219
	v_cvt_pk_fp8_f32 v249, v179, v254 op_sel:[0,0,1]
	ds_read_b128 v[122:125], v185 offset:36864
	ds_read_b128 v[126:129], v186 offset:36864
	s_waitcnt lgkmcnt(4)
	v_mfma_scale_f32_32x32x64_f8f6f4 v[82:97], v[114:121], v[138:145], v[82:97], v194, v193 op_sel_hi:[0,0,0]
	v_exp_f32_e32 v0, v98
	v_exp_f32_e32 v177, v99
	v_exp_f32_e32 v179, v100
	v_exp_f32_e32 v254, v101
	v_add_f32_e32 v219, v0, v219
	v_add_f32_e32 v219, v177, v219
	v_cvt_pk_fp8_f32 v250, v0, v177
	v_add_f32_e32 v219, v179, v219
	v_add_f32_e32 v219, v254, v219
	v_cvt_pk_fp8_f32 v250, v179, v254 op_sel:[0,0,1]
	s_waitcnt lgkmcnt(2)
	v_mfma_scale_f32_32x32x64_f8f6f4 v[66:81], v[222:229], v[138:145], v[66:81], v194, v193 op_sel_hi:[0,0,0]
	ds_read_b128 v[222:225], v185 offset:38912
	ds_read_b128 v[226:229], v186 offset:38912
	v_exp_f32_e32 v0, v102
	v_exp_f32_e32 v177, v103
	v_exp_f32_e32 v179, v104
	v_exp_f32_e32 v254, v105
	v_add_f32_e32 v219, v0, v219
	v_add_f32_e32 v219, v177, v219
	v_cvt_pk_fp8_f32 v251, v0, v177
	v_add_f32_e32 v219, v179, v219
	v_add_f32_e32 v219, v254, v219
	v_cvt_pk_fp8_f32 v251, v179, v254 op_sel:[0,0,1]
	v_exp_f32_e32 v0, v106
	v_exp_f32_e32 v177, v107
	v_exp_f32_e32 v179, v108
	v_exp_f32_e32 v254, v109
	v_add_f32_e32 v219, v0, v219
	v_add_f32_e32 v219, v177, v219
	v_cvt_pk_fp8_f32 v252, v0, v177
	v_add_f32_e32 v219, v179, v219
	v_add_f32_e32 v219, v254, v219
	v_cvt_pk_fp8_f32 v252, v179, v254 op_sel:[0,0,1]
	s_waitcnt lgkmcnt(2)
	v_mfma_scale_f32_32x32x64_f8f6f4 v[82:97], v[122:129], v[130:137], v[82:97], v194, v193 op_sel_hi:[0,0,0]
	v_exp_f32_e32 v0, v110
	v_exp_f32_e32 v177, v111
	v_exp_f32_e32 v179, v112
	v_exp_f32_e32 v254, v113
	v_add_f32_e32 v219, v0, v219
	v_add_f32_e32 v219, v177, v219
	v_cvt_pk_fp8_f32 v253, v0, v177
	v_add_f32_e32 v219, v179, v219
	v_add_f32_e32 v219, v254, v219
	v_cvt_pk_fp8_f32 v253, v179, v254 op_sel:[0,0,1]
	ds_read_b128 v[122:125], v185 offset:0
	ds_read_b128 v[126:129], v186 offset:0
	ds_read_b128 v[114:117], v185 offset:2048
	ds_read_b128 v[118:121], v186 offset:2048
	ds_read_b128 v[106:109], v185 offset:4096
	ds_read_b128 v[110:113], v186 offset:4096
	ds_read_b128 v[98:101], v185 offset:6144
	ds_read_b128 v[102:105], v186 offset:6144
	s_waitcnt lgkmcnt(8)
	v_mfma_scale_f32_32x32x64_f8f6f4 v[66:81], v[222:229], v[130:137], v[66:81], v194, v193 op_sel_hi:[0,0,0]
	v_mov_b32_e32 v0, v219
	s_nop 1
	v_permlane32_swap_b32_e32 v219, v0
	v_add_f32_e32 v219, v219, v0
	v_fma_f32 v209, v209, v221, v219
	v_max_f32_e32 v177, v82, v83
	v_max3_f32 v177, v177, v84, v85
	v_max3_f32 v177, v177, v86, v87
	v_max3_f32 v177, v177, v88, v89
	v_max3_f32 v177, v177, v90, v91
	v_max3_f32 v177, v177, v92, v93
	v_max3_f32 v177, v177, v94, v95
	v_max3_f32 v177, v177, v96, v97
	s_waitcnt lgkmcnt(6)
	v_mfma_scale_f32_32x32x64_f8f6f4 v[50:65], v[246:253], v[122:129], v[50:65], v194, v194 op_sel_hi:[0,0,0]
	s_waitcnt lgkmcnt(4)
	v_mfma_scale_f32_32x32x64_f8f6f4 v[34:49], v[246:253], v[114:121], v[34:49], v194, v194 op_sel_hi:[0,0,0]
	s_waitcnt lgkmcnt(2)
	v_mfma_scale_f32_32x32x64_f8f6f4 v[18:33], v[246:253], v[106:113], v[18:33], v194, v194 op_sel_hi:[0,0,0]
	s_waitcnt lgkmcnt(0)
	v_mfma_scale_f32_32x32x64_f8f6f4 v[2:17], v[246:253], v[98:105], v[2:17], v194, v194 op_sel_hi:[0,0,0]
	s_waitcnt vmcnt(0)
	ds_write_b128 v210, v[158:161] offset:43008
	ds_write_b128 v211, v[162:165] offset:51200
	s_and_saveexec_b64 s[20:21], s[42:43]
	ds_write_b128 v212, v[154:157] offset:59392
	s_or_b64 exec, exec, s[20:21]
	v_max_f32_e32 v0, v66, v67
	v_max3_f32 v0, v0, v68, v69
	v_max3_f32 v0, v0, v70, v71
	v_max3_f32 v0, v0, v72, v73
	v_max3_f32 v0, v0, v74, v75
	v_max3_f32 v0, v0, v76, v77
	v_max3_f32 v0, v0, v78, v79
	v_max3_f32 v0, v0, v80, v81
	v_max_f32_e32 v177, v177, v0
	v_mov_b32_e32 v0, v177
	v_mov_b32_e32 v218, 1.0
	s_nop 0
	v_permlane32_swap_b32_e32 v177, v0
	v_max_f32_e32 v177, v177, v0
	v_cmp_ge_f32_e32 vcc, s90, v177
	s_cmp_eq_u64 vcc, exec
	s_cbranch_scc0 .Lmla_h3_newmax

; __device__ __forceinline__ void pv8(f32x16* o, const char* Vt, const v8i32 p8, int r32, int hi) {
;   const int sw = (r32 >> 2) & 3, a0 = r32 * 64 + (((hi * 2) ^ sw) << 4), a1 = r32 * 64 + (((hi * 2 + 1) ^ sw) << 4);
; #pragma unroll
;   for (int d0 = 0; d0 < 4; ++d0) {
;     const v8i32 vf = cat8(*reinterpret_cast<const v4i32*>(Vt + d0 * 2048 + a0), *reinterpret_cast<const v4i32*>(Vt + d0 * 2048 + a1));
;     o[d0] = __builtin_amdgcn_mfma_scale_f32_32x32x64_f8f6f4(p8, vf, o[d0], 0, 0, 0, 127, 0, 127); }
; }
; __device__ __forceinline__ void qkt9(f32x16& p0, f32x16& p1, const char* Kn, const char* Kr, const v8i32* qf, const float init, int r32, int hi) {
; #pragma unroll
;   for (int r = 0; r < 16; ++r) { p0[r] = init; p1[r] = init; }
; #pragma unroll
;   for (int s = 0; s < 2; ++s) { const int c0 = s * 4 + hi * 2;
;     const v8i32 a0 = cat8(*reinterpret_cast<const v4i32*>(Kn + KN8SW(r32, c0)), *reinterpret_cast<const v4i32*>(Kn + KN8SW(r32, c0 + 1)));
;     const v8i32 a1 = cat8(*reinterpret_cast<const v4i32*>(Kn + 4096 + KN8SW(r32, c0)), *reinterpret_cast<const v4i32*>(Kn + 4096 + KN8SW(r32, c0 + 1)));
;     p0 = __builtin_amdgcn_mfma_scale_f32_32x32x64_f8f6f4(a0, qf[s], p0, 0, 0, 0, 127, 0, 124);
;     p1 = __builtin_amdgcn_mfma_scale_f32_32x32x64_f8f6f4(a1, qf[s], p1, 0, 0, 0, 127, 0, 124); }
;   { const int c0 = hi * 2;
;     const v8i32 a0 = cat8(*reinterpret_cast<const v4i32*>(Kr + KR8SW(r32, c0)), *reinterpret_cast<const v4i32*>(Kr + KR8SW(r32, c0 + 1)));
; __device__ __forceinline__ void attn_unit7(const unsigned char* __restrict__ Q8, int ldq, const unsigned char* __restrict__ Kn8, int ldk, const unsigned char* __restrict__ Kr8, ...
;     ...
;   for (int j = 1; j + 1 < NT; j += 2) {
;     SLOAD();
;     qkt9(pB0, pB1, Kn_lds + 8192, Kr_lds + 4096, qf, 7.0f - m_reg, r32, hi);
;     finishSM9(pA0, pA1, alA, l_reg, p8);
;     pv8(o, Vt_lds, p8, r32, hi); partialSM9(pB0, pB1, m_reg, alB, thr_raw);
;     __syncthreads(); SWRITE(0);
;     RESC(alB); __syncthreads();
;     if (j + 2 < NT) SLOAD();
;     qkt9(pA0, pA1, Kn_lds, Kr_lds, qf, 7.0f - m_reg, r32, hi);
;     finishSM9(pB0, pB1, alB, l_reg, p8);
;     pv8(o, Vt_lds + 8192, p8, r32, hi); partialSM9(pA0, pA1, m_reg, alA, thr_raw);
;     __syncthreads(); if (j + 2 < NT) SWRITE(1);
;     RESC(alA); __syncthreads();
.Lmla_h4_nokr:
	s_or_b64 exec, exec, s[20:21]
	ds_read_b128 v[114:117], v215 offset:51200
	ds_read_b128 v[118:121], v216 offset:51200
	ds_read_b128 v[222:225], v215 offset:55296
	ds_read_b128 v[226:229], v216 offset:55296
	v_add_u32_e32 v176, 0x2000, v176
	v_add_u32_e32 v178, 0x20000, v178
	s_mov_b64 s[20:21], 0x1000
	v_lshl_add_u64 v[180:181], v[180:181], 0, s[20:21]
	v_exp_f32_e32 v0, v82
	v_exp_f32_e32 v177, v83
	v_exp_f32_e32 v179, v84
	v_exp_f32_e32 v254, v85
	v_add_f32_e32 v219, v0, v177
	v_cvt_pk_fp8_f32 v246, v0, v177
	v_add_f32_e32 v219, v179, v219
	v_add_f32_e32 v219, v254, v219
	v_cvt_pk_fp8_f32 v246, v179, v254 op_sel:[0,0,1]
	s_waitcnt lgkmcnt(2)
	v_mfma_scale_f32_32x32x64_f8f6f4 v[114:129], v[114:121], v[146:153], v[230:245], v194, v193 op_sel_hi:[0,0,0]
	v_exp_f32_e32 v0, v86
	v_exp_f32_e32 v177, v87
	v_exp_f32_e32 v179, v88
	v_exp_f32_e32 v254, v89
	v_add_f32_e32 v219, v0, v219
	v_add_f32_e32 v219, v177, v219
	v_cvt_pk_fp8_f32 v247, v0, v177
	v_add_f32_e32 v219, v179, v219
	v_add_f32_e32 v219, v254, v219
	v_cvt_pk_fp8_f32 v247, v179, v254 op_sel:[0,0,1]
	ds_read_b128 v[82:85], v213 offset:51200
	ds_read_b128 v[86:89], v214 offset:51200
	s_waitcnt lgkmcnt(2)
	v_mfma_scale_f32_32x32x64_f8f6f4 v[98:113], v[222:229], v[146:153], v[230:245], v194, v193 op_sel_hi:[0,0,0]
	ds_read_b128 v[222:225], v213 offset:55296
	ds_read_b128 v[226:229], v214 offset:55296
	v_exp_f32_e32 v0, v90
	v_exp_f32_e32 v177, v91
	v_exp_f32_e32 v179, v92
	v_exp_f32_e32 v254, v93
	v_add_f32_e32 v219, v0, v219
	v_add_f32_e32 v219, v177, v219
	v_cvt_pk_fp8_f32 v248, v0, v177
	v_add_f32_e32 v219, v179, v219
	v_add_f32_e32 v219, v254, v219
	v_cvt_pk_fp8_f32 v248, v179, v254 op_sel:[0,0,1]
	v_exp_f32_e32 v0, v94
	v_exp_f32_e32 v177, v95
	v_exp_f32_e32 v179, v96
	v_exp_f32_e32 v254, v97
	v_add_f32_e32 v219, v0, v219
	v_add_f32_e32 v219, v177, v219
	v_cvt_pk_fp8_f32 v249, v0, v177
	v_add_f32_e32 v219, v179, v219
	v_add_f32_e32 v219, v254, v219
	v_cvt_pk_fp8_f32 v249, v179, v254 op_sel:[0,0,1]
	ds_read_b128 v[90:93], v185 offset:59392
	ds_read_b128 v[94:97], v186 offset:59392
	s_waitcnt lgkmcnt(4)
	v_mfma_scale_f32_32x32x64_f8f6f4 v[114:129], v[82:89], v[138:145], v[114:129], v194, v193 op_sel_hi:[0,0,0]
	v_exp_f32_e32 v0, v66
	v_exp_f32_e32 v177, v67
	v_exp_f32_e32 v179, v68
	v_exp_f32_e32 v254, v69
	v_add_f32_e32 v219, v0, v219
	v_add_f32_e32 v219, v177, v219
	v_cvt_pk_fp8_f32 v250, v0, v177
	v_add_f32_e32 v219, v179, v219
	v_add_f32_e32 v219, v254, v219
	v_cvt_pk_fp8_f32 v250, v179, v254 op_sel:[0,0,1]
	s_waitcnt lgkmcnt(2)
	v_mfma_scale_f32_32x32x64_f8f6f4 v[98:113], v[222:229], v[138:145], v[98:113], v194, v193 op_sel_hi:[0,0,0]
	ds_read_b128 v[222:225], v185 offset:61440
	ds_read_b128 v[226:229], v186 offset:61440
	v_exp_f32_e32 v0, v70
	v_exp_f32_e32 v177, v71
	v_exp_f32_e32 v179, v72
	v_exp_f32_e32 v254, v73
	v_add_f32_e32 v219, v0, v219
	v_add_f32_e32 v219, v177, v219
	v_cvt_pk_fp8_f32 v251, v0, v177
	v_add_f32_e32 v219, v179, v219
	v_add_f32_e32 v219, v254, v219
	v_cvt_pk_fp8_f32 v251, v179, v254 op_sel:[0,0,1]
	v_exp_f32_e32 v0, v74
	v_exp_f32_e32 v177, v75
	v_exp_f32_e32 v179, v76
	v_exp_f32_e32 v254, v77
	v_add_f32_e32 v219, v0, v219
	v_add_f32_e32 v219, v177, v219
	v_cvt_pk_fp8_f32 v252, v0, v177
	v_add_f32_e32 v219, v179, v219
	v_add_f32_e32 v219, v254, v219
	v_cvt_pk_fp8_f32 v252, v179, v254 op_sel:[0,0,1]
	s_waitcnt lgkmcnt(2)
	v_mfma_scale_f32_32x32x64_f8f6f4 v[114:129], v[90:97], v[130:137], v[114:129], v194, v193 op_sel_hi:[0,0,0]
	v_exp_f32_e32 v0, v78
	v_exp_f32_e32 v177, v79
	v_exp_f32_e32 v179, v80
	v_exp_f32_e32 v254, v81
	v_add_f32_e32 v219, v0, v219
	v_add_f32_e32 v219, v177, v219
	v_cvt_pk_fp8_f32 v253, v0, v177
	v_add_f32_e32 v219, v179, v219
	v_add_f32_e32 v219, v254, v219
	v_cvt_pk_fp8_f32 v253, v179, v254 op_sel:[0,0,1]
	ds_read_b128 v[90:93], v185 offset:8192
	ds_read_b128 v[94:97], v186 offset:8192
	ds_read_b128 v[82:85], v185 offset:10240
	ds_read_b128 v[86:89], v186 offset:10240
	ds_read_b128 v[74:77], v185 offset:12288
	ds_read_b128 v[78:81], v186 offset:12288
	ds_read_b128 v[66:69], v185 offset:14336
	ds_read_b128 v[70:73], v186 offset:14336
	s_waitcnt lgkmcnt(8)
	v_mfma_scale_f32_32x32x64_f8f6f4 v[98:113], v[222:229], v[130:137], v[98:113], v194, v193 op_sel_hi:[0,0,0]
	v_mov_b32_e32 v0, v219
	s_nop 1
	v_permlane32_swap_b32_e32 v219, v0
	v_add_f32_e32 v219, v219, v0
	v_fma_f32 v209, v209, v218, v219
	v_max_f32_e32 v177, v114, v115
	v_max3_f32 v177, v177, v116, v117
	v_max3_f32 v177, v177, v118, v119
	v_max3_f32 v177, v177, v120, v121
	v_max3_f32 v177, v177, v122, v123
	v_max3_f32 v177, v177, v124, v125
	v_max3_f32 v177, v177, v126, v127
	v_max3_f32 v177, v177, v128, v129
	s_waitcnt lgkmcnt(6)
	v_mfma_scale_f32_32x32x64_f8f6f4 v[50:65], v[246:253], v[90:97], v[50:65], v194, v194 op_sel_hi:[0,0,0]
	s_waitcnt lgkmcnt(4)
	v_mfma_scale_f32_32x32x64_f8f6f4 v[34:49], v[246:253], v[82:89], v[34:49], v194, v194 op_sel_hi:[0,0,0]
	s_waitcnt lgkmcnt(2)
	v_mfma_scale_f32_32x32x64_f8f6f4 v[18:33], v[246:253], v[74:81], v[18:33], v194, v194 op_sel_hi:[0,0,0]
	s_waitcnt lgkmcnt(0)
	v_mfma_scale_f32_32x32x64_f8f6f4 v[2:17], v[246:253], v[66:73], v[2:17], v194, v194 op_sel_hi:[0,0,0]
	s_waitcnt vmcnt(0)
	ds_write_b128 v210, v[158:161]
	ds_write_b128 v211, v[162:165] offset:16384
	s_and_saveexec_b64 s[20:21], s[42:43]
	ds_write_b128 v212, v[154:157] offset:32768
	s_or_b64 exec, exec, s[20:21]
	v_max_f32_e32 v0, v98, v99
	v_max3_f32 v0, v0, v100, v101
	v_max3_f32 v0, v0, v102, v103
	v_max3_f32 v0, v0, v104, v105
	v_max3_f32 v0, v0, v106, v107
	v_max3_f32 v0, v0, v108, v109
	v_max3_f32 v0, v0, v110, v111
	v_max3_f32 v0, v0, v112, v113
	v_max_f32_e32 v177, v177, v0
	v_mov_b32_e32 v0, v177
	v_mov_b32_e32 v221, 1.0
	s_nop 0
	v_permlane32_swap_b32_e32 v177, v0
	v_max_f32_e32 v177, v177, v0
	v_cmp_ge_f32_e32 vcc, s90, v177
	s_cmp_eq_u64 vcc, exec
	s_cbranch_scc0 .Lmla_h4_newmax

; __device__ __forceinline__ void pv8(f32x16* o, const char* Vt, const v8i32 p8, int r32, int hi) {
;   const int sw = (r32 >> 2) & 3, a0 = r32 * 64 + (((hi * 2) ^ sw) << 4), a1 = r32 * 64 + (((hi * 2 + 1) ^ sw) << 4);
; #pragma unroll
;   for (int d0 = 0; d0 < 4; ++d0) {
;     const v8i32 vf = cat8(*reinterpret_cast<const v4i32*>(Vt + d0 * 2048 + a0), *reinterpret_cast<const v4i32*>(Vt + d0 * 2048 + a1));
;     o[d0] = __builtin_amdgcn_mfma_scale_f32_32x32x64_f8f6f4(p8, vf, o[d0], 0, 0, 0, 127, 0, 127); }
; }
; __device__ __forceinline__ void qkt9(f32x16& p0, f32x16& p1, const char* Kn, const char* Kr, const v8i32* qf, const float init, int r32, int hi) {
; #pragma unroll
;   for (int r = 0; r < 16; ++r) { p0[r] = init; p1[r] = init; }
; #pragma unroll
;   for (int s = 0; s < 2; ++s) { const int c0 = s * 4 + hi * 2;
;     const v8i32 a0 = cat8(*reinterpret_cast<const v4i32*>(Kn + KN8SW(r32, c0)), *reinterpret_cast<const v4i32*>(Kn + KN8SW(r32, c0 + 1)));
;     const v8i32 a1 = cat8(*reinterpret_cast<const v4i32*>(Kn + 4096 + KN8SW(r32, c0)), *reinterpret_cast<const v4i32*>(Kn + 4096 + KN8SW(r32, c0 + 1)));
;     p0 = __builtin_amdgcn_mfma_scale_f32_32x32x64_f8f6f4(a0, qf[s], p0, 0, 0, 0, 127, 0, 124);
;     p1 = __builtin_amdgcn_mfma_scale_f32_32x32x64_f8f6f4(a1, qf[s], p1, 0, 0, 0, 127, 0, 124); }
;   { const int c0 = hi * 2;
;     const v8i32 a0 = cat8(*reinterpret_cast<const v4i32*>(Kr + KR8SW(r32, c0)), *reinterpret_cast<const v4i32*>(Kr + KR8SW(r32, c0 + 1)));
; __device__ __forceinline__ void attn_unit7(const unsigned char* __restrict__ Q8, int ldq, const unsigned char* __restrict__ Kn8, int ldk, const unsigned char* __restrict__ Kr8, ...
;     ...
;   for (int j = 1; j + 1 < NT; j += 2) {
;     SLOAD();
;     qkt9(pB0, pB1, Kn_lds + 8192, Kr_lds + 4096, qf, 7.0f - m_reg, r32, hi);
;     finishSM9(pA0, pA1, alA, l_reg, p8);
;     pv8(o, Vt_lds, p8, r32, hi); partialSM9(pB0, pB1, m_reg, alB, thr_raw);
;     __syncthreads(); SWRITE(0);
;     RESC(alB); __syncthreads();
;     if (j + 2 < NT) SLOAD();
;     qkt9(pA0, pA1, Kn_lds, Kr_lds, qf, 7.0f - m_reg, r32, hi);
;     finishSM9(pB0, pB1, alB, l_reg, p8);
;     pv8(o, Vt_lds + 8192, p8, r32, hi); partialSM9(pA0, pA1, m_reg, alA, thr_raw);
;     __syncthreads(); if (j + 2 < NT) SWRITE(1);
;     RESC(alA); __syncthreads();
;   }
.Lmla_h5_nokr:
	s_or_b64 exec, exec, s[20:21]
	ds_read_b128 v[82:85], v215 offset:16384
	ds_read_b128 v[86:89], v216 offset:16384
	ds_read_b128 v[222:225], v215 offset:20480
	ds_read_b128 v[226:229], v216 offset:20480
	v_add_u32_e32 v176, 0x2000, v176
	v_add_u32_e32 v178, 0x20000, v178
	s_mov_b64 s[20:21], 0x1000
	v_lshl_add_u64 v[180:181], v[180:181], 0, s[20:21]
	v_exp_f32_e32 v0, v114
	v_exp_f32_e32 v177, v115
	v_exp_f32_e32 v179, v116
	v_exp_f32_e32 v254, v117
	v_add_f32_e32 v219, v0, v177
	v_cvt_pk_fp8_f32 v246, v0, v177
	v_add_f32_e32 v219, v179, v219
	v_add_f32_e32 v219, v254, v219
	v_cvt_pk_fp8_f32 v246, v179, v254 op_sel:[0,0,1]
	s_waitcnt lgkmcnt(2)
	v_mfma_scale_f32_32x32x64_f8f6f4 v[82:97], v[82:89], v[146:153], v[230:245], v194, v193 op_sel_hi:[0,0,0]
	v_exp_f32_e32 v0, v118
	v_exp_f32_e32 v177, v119
	v_exp_f32_e32 v179, v120
	v_exp_f32_e32 v254, v121
	v_add_f32_e32 v219, v0, v219
	v_add_f32_e32 v219, v177, v219
	v_cvt_pk_fp8_f32 v247, v0, v177
	v_add_f32_e32 v219, v179, v219
	v_add_f32_e32 v219, v254, v219
	v_cvt_pk_fp8_f32 v247, v179, v254 op_sel:[0,0,1]
	ds_read_b128 v[114:117], v213 offset:16384
	ds_read_b128 v[118:121], v214 offset:16384
	s_waitcnt lgkmcnt(2)
	v_mfma_scale_f32_32x32x64_f8f6f4 v[66:81], v[222:229], v[146:153], v[230:245], v194, v193 op_sel_hi:[0,0,0]
	ds_read_b128 v[222:225], v213 offset:20480
	ds_read_b128 v[226:229], v214 offset:20480
	v_exp_f32_e32 v0, v122
	v_exp_f32_e32 v177, v123
	v_exp_f32_e32 v179, v124
	v_exp_f32_e32 v254, v125
	v_add_f32_e32 v219, v0, v219
	v_add_f32_e32 v219, v177, v219
	v_cvt_pk_fp8_f32 v248, v0, v177
	v_add_f32_e32 v219, v179, v219
	v_add_f32_e32 v219, v254, v219
	v_cvt_pk_fp8_f32 v248, v179, v254 op_sel:[0,0,1]
	v_exp_f32_e32 v0, v126
	v_exp_f32_e32 v177, v127
	v_exp_f32_e32 v179, v128
	v_exp_f32_e32 v254, v129
	v_add_f32_e32 v219, v0, v219
	v_add_f32_e32 v219, v177, v219
	v_cvt_pk_fp8_f32 v249, v0, v177
	v_add_f32_e32 v219, v179, v219
	v_add_f32_e32 v219, v254, v219
	v_cvt_pk_fp8_f32 v249, v179, v254 op_sel:[0,0,1]
	ds_read_b128 v[122:125], v185 offset:32768
	ds_read_b128 v[126:129], v186 offset:32768
	s_waitcnt lgkmcnt(4)
	v_mfma_scale_f32_32x32x64_f8f6f4 v[82:97], v[114:121], v[138:145], v[82:97], v194, v193 op_sel_hi:[0,0,0]
	v_exp_f32_e32 v0, v98
	v_exp_f32_e32 v177, v99
	v_exp_f32_e32 v179, v100
	v_exp_f32_e32 v254, v101
	v_add_f32_e32 v219, v0, v219
	v_add_f32_e32 v219, v177, v219
	v_cvt_pk_fp8_f32 v250, v0, v177
	v_add_f32_e32 v219, v179, v219
	v_add_f32_e32 v219, v254, v219
	v_cvt_pk_fp8_f32 v250, v179, v254 op_sel:[0,0,1]
	s_waitcnt lgkmcnt(2)
	v_mfma_scale_f32_32x32x64_f8f6f4 v[66:81], v[222:229], v[138:145], v[66:81], v194, v193 op_sel_hi:[0,0,0]
	ds_read_b128 v[222:225], v185 offset:34816
	ds_read_b128 v[226:229], v186 offset:34816
	v_exp_f32_e32 v0, v102
	v_exp_f32_e32 v177, v103
	v_exp_f32_e32 v179, v104
	v_exp_f32_e32 v254, v105
	v_add_f32_e32 v219, v0, v219
	v_add_f32_e32 v219, v177, v219
	v_cvt_pk_fp8_f32 v251, v0, v177
	v_add_f32_e32 v219, v179, v219
	v_add_f32_e32 v219, v254, v219
	v_cvt_pk_fp8_f32 v251, v179, v254 op_sel:[0,0,1]
	v_exp_f32_e32 v0, v106
	v_exp_f32_e32 v177, v107
	v_exp_f32_e32 v179, v108
	v_exp_f32_e32 v254, v109
	v_add_f32_e32 v219, v0, v219
	v_add_f32_e32 v219, v177, v219
	v_cvt_pk_fp8_f32 v252, v0, v177
	v_add_f32_e32 v219, v179, v219
	v_add_f32_e32 v219, v254, v219
	v_cvt_pk_fp8_f32 v252, v179, v254 op_sel:[0,0,1]
	s_waitcnt lgkmcnt(2)
	v_mfma_scale_f32_32x32x64_f8f6f4 v[82:97], v[122:129], v[130:137], v[82:97], v194, v193 op_sel_hi:[0,0,0]
	v_exp_f32_e32 v0, v110
	v_exp_f32_e32 v177, v111
	v_exp_f32_e32 v179, v112
	v_exp_f32_e32 v254, v113
	v_add_f32_e32 v219, v0, v219
	v_add_f32_e32 v219, v177, v219
	v_cvt_pk_fp8_f32 v253, v0, v177
	v_add_f32_e32 v219, v179, v219
	v_add_f32_e32 v219, v254, v219
	v_cvt_pk_fp8_f32 v253, v179, v254 op_sel:[0,0,1]
	ds_read_b128 v[122:125], v185 offset:43008
	ds_read_b128 v[126:129], v186 offset:43008
	ds_read_b128 v[114:117], v185 offset:45056
	ds_read_b128 v[118:121], v186 offset:45056
	ds_read_b128 v[106:109], v185 offset:47104
	ds_read_b128 v[110:113], v186 offset:47104
	ds_read_b128 v[98:101], v185 offset:49152
	ds_read_b128 v[102:105], v186 offset:49152
	s_waitcnt lgkmcnt(8)
	v_mfma_scale_f32_32x32x64_f8f6f4 v[66:81], v[222:229], v[130:137], v[66:81], v194, v193 op_sel_hi:[0,0,0]
	v_mov_b32_e32 v0, v219
	s_nop 1
	v_permlane32_swap_b32_e32 v219, v0
	v_add_f32_e32 v219, v219, v0
	v_fma_f32 v209, v209, v221, v219
	v_max_f32_e32 v177, v82, v83
	v_max3_f32 v177, v177, v84, v85
	v_max3_f32 v177, v177, v86, v87
	v_max3_f32 v177, v177, v88, v89
	v_max3_f32 v177, v177, v90, v91
	v_max3_f32 v177, v177, v92, v93
	v_max3_f32 v177, v177, v94, v95
	v_max3_f32 v177, v177, v96, v97
	s_waitcnt lgkmcnt(6)
	v_mfma_scale_f32_32x32x64_f8f6f4 v[50:65], v[246:253], v[122:129], v[50:65], v194, v194 op_sel_hi:[0,0,0]
	s_waitcnt lgkmcnt(4)
	v_mfma_scale_f32_32x32x64_f8f6f4 v[34:49], v[246:253], v[114:121], v[34:49], v194, v194 op_sel_hi:[0,0,0]
	s_waitcnt lgkmcnt(2)
	v_mfma_scale_f32_32x32x64_f8f6f4 v[18:33], v[246:253], v[106:113], v[18:33], v194, v194 op_sel_hi:[0,0,0]
	s_waitcnt lgkmcnt(0)
	v_mfma_scale_f32_32x32x64_f8f6f4 v[2:17], v[246:253], v[98:105], v[2:17], v194, v194 op_sel_hi:[0,0,0]
	s_waitcnt vmcnt(0)
	ds_write_b128 v210, v[158:161] offset:8192
	ds_write_b128 v211, v[162:165] offset:24576
	s_and_saveexec_b64 s[20:21], s[42:43]
	ds_write_b128 v212, v[154:157] offset:36864
	s_or_b64 exec, exec, s[20:21]
	v_max_f32_e32 v0, v66, v67
	v_max3_f32 v0, v0, v68, v69
	v_max3_f32 v0, v0, v70, v71
	v_max3_f32 v0, v0, v72, v73
	v_max3_f32 v0, v0, v74, v75
	v_max3_f32 v0, v0, v76, v77
	v_max3_f32 v0, v0, v78, v79
	v_max3_f32 v0, v0, v80, v81
	v_max_f32_e32 v177, v177, v0
	v_mov_b32_e32 v0, v177
	v_mov_b32_e32 v218, 1.0
	s_nop 0
	v_permlane32_swap_b32_e32 v177, v0
	v_max_f32_e32 v177, v177, v0
	v_cmp_ge_f32_e32 vcc, s90, v177
	s_cmp_eq_u64 vcc, exec
	s_cbranch_scc0 .Lmla_h5_newmax
.Lmla_h5_cont:
	s_waitcnt lgkmcnt(0)
	s_barrier
	s_add_i32 s30, s30, 1
	s_cmpk_lt_u32 s30, 42
	s_cbranch_scc1 .LBB0_1321
	global_load_dwordx4 v[158:161], v176, s[18:19]
	global_load_dwordx4 v[162:165], v178, s[16:17]
	s_and_saveexec_b64 s[20:21], s[42:43]
	s_cbranch_execz .Lmla_p0_nokr
	global_load_dwordx4 v[154:157], v[180:181], off

; #define SLOAD() do { vs0 = *(const bf16x8*)(Vh + voff); vs1 = *(const bf16x8*)(Vh + voff + 32u * (unsigned)ldv); \
;     ks0 = *(const bf16x8*)(Kh + koff); ks1 = *(const bf16x8*)(Kh + koff + 32u * (unsigned)ldk); \
;     if constexpr (NR > 0) { kr = *(const bf16x8*)(Krh + kroff); kroff += 64u * 64u; } voff += 64u * (unsigned)ldv; koff += 64u * (unsigned)ldk; } while (0)
; #define SWRITE(b) do { *(bf16x8*)(V_lds + (b) * SHM_V + vst0) = vs0; *(bf16x8*)(V_lds + (b) * SHM_V + vst1) = vs1; const int kc = sc * 2;  \
;     *(bf16x8*)(K_lds + (b) * SHM_K + KSWZ(sr, kc)) = ks0; *(bf16x8*)(K_lds + (b) * SHM_K + KSWZ(32 + sr, kc)) = ks1; \
;     if constexpr (NR > 0) *(bf16x8*)(Kr_lds + (b) * SHM_KR + krst) = kr; } while (0)
; #define SLOAD() do { vs0 = *(const bf16x8*)(Vh + voff); vs1 = *(const bf16x8*)(Vh + voff + 32u * (unsigned)ldv); \
;     ks0 = *(const bf16x8*)(Kh + voff); ks1 = *(const bf16x8*)(Kh + voff + 32u * (unsigned)ldv); \
;     if constexpr (NR > 0) { kr = *(const bf16x8*)(Krh + kroff); kroff += 64u * 64u; } voff += 64u * (unsigned)ldv; } while (0)
; #define SWRITE(b) do { *(bf16x8*)(V_lds + (b) * SHM_V + vst0) = vs0; *(bf16x8*)(V_lds + (b) * SHM_V + vst0 + 8192) = vs1;  \
;     *(bf16x8*)(K_lds + (b) * SHM_K + kst0) = ks0; *(bf16x8*)(K_lds + (b) * SHM_K + kst0 + 8192) = ks1; \
;     if constexpr (NR > 0) *(bf16x8*)(Kr_lds + (b) * SHM_KR + krst) = kr; } while (0)
; #define SWRITE(b) do { *(v4i32*)(Vt_lds + (b) * 8192 + vtst) = vt; *(v4i32*)(Kn_lds + (b) * 8192 + knst) = kn; if (krw) *(v4i32*)(Kr_lds + (b) * 4096 + krst) = kr; } while (0)
; __device__ __forceinline__ void attn_unit7(const unsigned char* __restrict__ Q8, int ldq, const unsigned char* __restrict__ Kn8, int ldk, const unsigned char* __restrict__ Kr8, ...
;     ...
;   for (int j = 1; j + 1 < NT; j += 2) {
;     SLOAD();
;     qkt9(pB0, pB1, Kn_lds + 8192, Kr_lds + 4096, qf, 7.0f - m_reg, r32, hi);
;     finishSM9(pA0, pA1, alA, l_reg, p8);
;     pv8(o, Vt_lds, p8, r32, hi); partialSM9(pB0, pB1, m_reg, alB, thr_raw);
;     __syncthreads(); SWRITE(0);
;     RESC(alB); __syncthreads();
;     if (j + 2 < NT) SLOAD();
;     qkt9(pA0, pA1, Kn_lds, Kr_lds, qf, 7.0f - m_reg, r32, hi);
;     finishSM9(pB0, pB1, alB, l_reg, p8);
;     pv8(o, Vt_lds + 8192, p8, r32, hi); partialSM9(pA0, pA1, m_reg, alA, thr_raw);
;     __syncthreads(); if (j + 2 < NT) SWRITE(1);
;     RESC(alA); __syncthreads();
;   }
.Lmla_p1_cont:
	v_mov_b32_e32 v0, v218
	s_waitcnt lgkmcnt(0)
	s_barrier
	s_branch .LBB0_1343

; __device__ __forceinline__ void partialSM9(f32x16& p0, f32x16& p1, float& m_run, float& alpha, const float thr2) {
;   float pmax = p0[0];
; #pragma unroll
;   for (int r = 1; r < 16; ++r) pmax = fmaxf(pmax, p0[r]);
; #pragma unroll
;   for (int r = 0; r < 16; ++r) pmax = fmaxf(pmax, p1[r]);
;   { auto rr = __builtin_amdgcn_permlane32_swap(__float_as_uint(pmax), __float_as_uint(pmax), false, false);
;     pmax = fmaxf(__uint_as_float(rr[0]), __uint_as_float(rr[1])); }
;   if (__builtin_expect(__all(pmax <= 7.0f + thr2), 1)) { alpha = 1.f; }
;   else { const float delta = fmaxf(pmax - 7.0f, 0.f); alpha = __builtin_amdgcn_exp2f(-delta); m_run += delta;
; #pragma unroll
;     for (int r = 0; r < 16; ++r) { p0[r] -= delta; p1[r] -= delta; } }
; }
.Lmla_h1_newmax:
	v_add_f32_e32 v0, 0xc0e00000, v177
	v_max_f32_e32 v177, 0, v0
	v_exp_f32_e64 v218, -v177
	v_add_f32_e32 v217, v217, v177
	v_sub_f32_e32 v97, v97, v177
	v_sub_f32_e32 v96, v96, v177
	v_sub_f32_e32 v95, v95, v177
	v_sub_f32_e32 v94, v94, v177
	v_sub_f32_e32 v93, v93, v177
	v_sub_f32_e32 v92, v92, v177
	v_sub_f32_e32 v91, v91, v177
	v_sub_f32_e32 v90, v90, v177
	v_sub_f32_e32 v89, v89, v177
	v_sub_f32_e32 v88, v88, v177
	v_sub_f32_e32 v87, v87, v177
	v_sub_f32_e32 v86, v86, v177
	v_sub_f32_e32 v85, v85, v177
	v_sub_f32_e32 v84, v84, v177
	v_sub_f32_e32 v83, v83, v177
	v_sub_f32_e32 v82, v82, v177
	s_and_saveexec_b64 s[20:21], s[40:41]
	ds_write_b32 v208, v218 offset:41088
	s_or_b64 exec, exec, s[20:21]
	v_sub_f32_e32 v81, v81, v177
	v_sub_f32_e32 v80, v80, v177
	v_sub_f32_e32 v79, v79, v177
	v_sub_f32_e32 v78, v78, v177
	v_sub_f32_e32 v77, v77, v177
	v_sub_f32_e32 v76, v76, v177
	v_sub_f32_e32 v75, v75, v177
	v_sub_f32_e32 v74, v74, v177
	v_sub_f32_e32 v73, v73, v177
	v_sub_f32_e32 v72, v72, v177
	v_sub_f32_e32 v71, v71, v177
	v_sub_f32_e32 v70, v70, v177
	v_sub_f32_e32 v69, v69, v177
	v_sub_f32_e32 v68, v68, v177
	v_sub_f32_e32 v67, v67, v177
	v_sub_f32_e32 v66, v66, v177
	v_sub_f32_e32 v230, 0x40e00000, v217
	v_mov_b32_e32 v231, v230
	v_mov_b32_e32 v232, v230
	v_mov_b32_e32 v233, v230
	v_mov_b32_e32 v234, v230
	v_mov_b32_e32 v235, v230
	v_mov_b32_e32 v236, v230
	v_mov_b32_e32 v237, v230
	v_mov_b32_e32 v238, v230
	v_mov_b32_e32 v239, v230
	v_mov_b32_e32 v240, v230
	v_mov_b32_e32 v241, v230
	v_mov_b32_e32 v242, v230
	v_mov_b32_e32 v243, v230
	v_mov_b32_e32 v244, v230
	v_mov_b32_e32 v245, v230
	v_add_u32_e32 v0, v187, v207
	s_waitcnt lgkmcnt(0)
	ds_read_b128 v[98:101], v0 offset:41184
	ds_read_b128 v[102:105], v0 offset:41152
	ds_read_b128 v[106:109], v0 offset:41120
	ds_read_b128 v[110:113], v0 offset:41088
	s_waitcnt lgkmcnt(0)
	v_pk_mul_f32 v[62:63], v[62:63], v[98:99]
	v_pk_mul_f32 v[58:59], v[58:59], v[102:103]
	v_pk_mul_f32 v[54:55], v[54:55], v[106:107]
	v_pk_mul_f32 v[64:65], v[64:65], v[100:101]
	v_pk_mul_f32 v[60:61], v[60:61], v[104:105]
	v_pk_mul_f32 v[56:57], v[56:57], v[108:109]
	v_pk_mul_f32 v[52:53], v[52:53], v[112:113]
	v_pk_mul_f32 v[50:51], v[50:51], v[110:111]
	v_pk_mul_f32 v[46:47], v[46:47], v[98:99]
	v_pk_mul_f32 v[42:43], v[42:43], v[102:103]
	v_pk_mul_f32 v[38:39], v[38:39], v[106:107]
	v_pk_mul_f32 v[48:49], v[48:49], v[100:101]
	v_pk_mul_f32 v[44:45], v[44:45], v[104:105]
	v_pk_mul_f32 v[40:41], v[40:41], v[108:109]
	v_pk_mul_f32 v[36:37], v[36:37], v[112:113]
	v_pk_mul_f32 v[34:35], v[34:35], v[110:111]
	v_pk_mul_f32 v[30:31], v[30:31], v[98:99]
	v_pk_mul_f32 v[26:27], v[26:27], v[102:103]
	v_pk_mul_f32 v[22:23], v[22:23], v[106:107]
	v_pk_mul_f32 v[32:33], v[32:33], v[100:101]
	v_pk_mul_f32 v[28:29], v[28:29], v[104:105]
	v_pk_mul_f32 v[24:25], v[24:25], v[108:109]
	v_pk_mul_f32 v[20:21], v[20:21], v[112:113]
	v_pk_mul_f32 v[18:19], v[18:19], v[110:111]
	v_pk_mul_f32 v[14:15], v[14:15], v[98:99]
	v_pk_mul_f32 v[10:11], v[10:11], v[102:103]
	v_pk_mul_f32 v[6:7], v[6:7], v[106:107]
	v_pk_mul_f32 v[16:17], v[16:17], v[100:101]
	v_pk_mul_f32 v[12:13], v[12:13], v[104:105]
	v_pk_mul_f32 v[8:9], v[8:9], v[108:109]
	v_pk_mul_f32 v[4:5], v[4:5], v[112:113]
	v_pk_mul_f32 v[2:3], v[2:3], v[110:111]
	s_branch .Lmla_h1_cont
.Lmla_h2_newmax:
	v_add_f32_e32 v0, 0xc0e00000, v177
	v_max_f32_e32 v177, 0, v0
	v_exp_f32_e64 v221, -v177
	v_add_f32_e32 v217, v217, v177
	v_sub_f32_e32 v129, v129, v177
	v_sub_f32_e32 v128, v128, v177
	v_sub_f32_e32 v127, v127, v177
	v_sub_f32_e32 v126, v126, v177
	v_sub_f32_e32 v125, v125, v177
	v_sub_f32_e32 v124, v124, v177
	v_sub_f32_e32 v123, v123, v177
	v_sub_f32_e32 v122, v122, v177
	v_sub_f32_e32 v121, v121, v177
	v_sub_f32_e32 v120, v120, v177
	v_sub_f32_e32 v119, v119, v177
	v_sub_f32_e32 v118, v118, v177
	v_sub_f32_e32 v117, v117, v177
	v_sub_f32_e32 v116, v116, v177
	v_sub_f32_e32 v115, v115, v177
	v_sub_f32_e32 v114, v114, v177
	s_and_saveexec_b64 s[20:21], s[40:41]
	ds_write_b32 v208, v221 offset:41088
	s_or_b64 exec, exec, s[20:21]
	v_sub_f32_e32 v113, v113, v177
	v_sub_f32_e32 v112, v112, v177
	v_sub_f32_e32 v111, v111, v177
	v_sub_f32_e32 v110, v110, v177
	v_sub_f32_e32 v109, v109, v177
	v_sub_f32_e32 v108, v108, v177
	v_sub_f32_e32 v107, v107, v177
	v_sub_f32_e32 v106, v106, v177
	v_sub_f32_e32 v105, v105, v177
	v_sub_f32_e32 v104, v104, v177
	v_sub_f32_e32 v103, v103, v177
	v_sub_f32_e32 v102, v102, v177
	v_sub_f32_e32 v101, v101, v177
	v_sub_f32_e32 v100, v100, v177
	v_sub_f32_e32 v99, v99, v177
	v_sub_f32_e32 v98, v98, v177
	v_sub_f32_e32 v230, 0x40e00000, v217
	v_mov_b32_e32 v231, v230
	v_mov_b32_e32 v232, v230
	v_mov_b32_e32 v233, v230
	v_mov_b32_e32 v234, v230
	v_mov_b32_e32 v235, v230
	v_mov_b32_e32 v236, v230
	v_mov_b32_e32 v237, v230
	v_mov_b32_e32 v238, v230
	v_mov_b32_e32 v239, v230
	v_mov_b32_e32 v240, v230
	v_mov_b32_e32 v241, v230
	v_mov_b32_e32 v242, v230
	v_mov_b32_e32 v243, v230
	v_mov_b32_e32 v244, v230
	v_mov_b32_e32 v245, v230
	v_add_u32_e32 v0, v187, v207
	s_waitcnt lgkmcnt(0)
	ds_read_b128 v[66:69], v0 offset:41184
	ds_read_b128 v[70:73], v0 offset:41152
	ds_read_b128 v[74:77], v0 offset:41120
	ds_read_b128 v[78:81], v0 offset:41088
	s_waitcnt lgkmcnt(0)
	v_pk_mul_f32 v[62:63], v[62:63], v[66:67]
	v_pk_mul_f32 v[58:59], v[58:59], v[70:71]
	v_pk_mul_f32 v[54:55], v[54:55], v[74:75]
	v_pk_mul_f32 v[64:65], v[64:65], v[68:69]
	v_pk_mul_f32 v[60:61], v[60:61], v[72:73]
	v_pk_mul_f32 v[56:57], v[56:57], v[76:77]
	v_pk_mul_f32 v[52:53], v[52:53], v[80:81]
	v_pk_mul_f32 v[50:51], v[50:51], v[78:79]
	v_pk_mul_f32 v[46:47], v[46:47], v[66:67]
	v_pk_mul_f32 v[42:43], v[42:43], v[70:71]
	v_pk_mul_f32 v[38:39], v[38:39], v[74:75]
	v_pk_mul_f32 v[48:49], v[48:49], v[68:69]
	v_pk_mul_f32 v[44:45], v[44:45], v[72:73]
	v_pk_mul_f32 v[40:41], v[40:41], v[76:77]
	v_pk_mul_f32 v[36:37], v[36:37], v[80:81]
	v_pk_mul_f32 v[34:35], v[34:35], v[78:79]
	v_pk_mul_f32 v[30:31], v[30:31], v[66:67]
	v_pk_mul_f32 v[26:27], v[26:27], v[70:71]
	v_pk_mul_f32 v[22:23], v[22:23], v[74:75]
	v_pk_mul_f32 v[32:33], v[32:33], v[68:69]
	v_pk_mul_f32 v[28:29], v[28:29], v[72:73]
	v_pk_mul_f32 v[24:25], v[24:25], v[76:77]
	v_pk_mul_f32 v[20:21], v[20:21], v[80:81]
	v_pk_mul_f32 v[18:19], v[18:19], v[78:79]
	v_pk_mul_f32 v[14:15], v[14:15], v[66:67]
	v_pk_mul_f32 v[10:11], v[10:11], v[70:71]
	v_pk_mul_f32 v[6:7], v[6:7], v[74:75]
	v_pk_mul_f32 v[16:17], v[16:17], v[68:69]
	v_pk_mul_f32 v[12:13], v[12:13], v[72:73]
	v_pk_mul_f32 v[8:9], v[8:9], v[76:77]
	v_pk_mul_f32 v[4:5], v[4:5], v[80:81]
	v_pk_mul_f32 v[2:3], v[2:3], v[78:79]
	s_branch .Lmla_h2_cont
; __device__ __forceinline__ void partialSM9(f32x16& p0, f32x16& p1, float& m_run, float& alpha, const float thr2) {
;   float pmax = p0[0];
; #pragma unroll
;   for (int r = 1; r < 16; ++r) pmax = fmaxf(pmax, p0[r]);
; #pragma unroll
;   for (int r = 0; r < 16; ++r) pmax = fmaxf(pmax, p1[r]);
;   { auto rr = __builtin_amdgcn_permlane32_swap(__float_as_uint(pmax), __float_as_uint(pmax), false, false);
;     pmax = fmaxf(__uint_as_float(rr[0]), __uint_as_float(rr[1])); }
;   if (__builtin_expect(__all(pmax <= 7.0f + thr2), 1)) { alpha = 1.f; }
;   else { const float delta = fmaxf(pmax - 7.0f, 0.f); alpha = __builtin_amdgcn_exp2f(-delta); m_run += delta;
; #pragma unroll
;     for (int r = 0; r < 16; ++r) { p0[r] -= delta; p1[r] -= delta; } }
; }
.Lmla_h3_newmax:
	v_add_f32_e32 v0, 0xc0e00000, v177
	v_max_f32_e32 v177, 0, v0
	v_exp_f32_e64 v218, -v177
	v_add_f32_e32 v217, v217, v177
	v_sub_f32_e32 v97, v97, v177
	v_sub_f32_e32 v96, v96, v177
	v_sub_f32_e32 v95, v95, v177
	v_sub_f32_e32 v94, v94, v177
	v_sub_f32_e32 v93, v93, v177
	v_sub_f32_e32 v92, v92, v177
	v_sub_f32_e32 v91, v91, v177
	v_sub_f32_e32 v90, v90, v177
	v_sub_f32_e32 v89, v89, v177
	v_sub_f32_e32 v88, v88, v177
	v_sub_f32_e32 v87, v87, v177
	v_sub_f32_e32 v86, v86, v177
	v_sub_f32_e32 v85, v85, v177
	v_sub_f32_e32 v84, v84, v177
	v_sub_f32_e32 v83, v83, v177
	v_sub_f32_e32 v82, v82, v177
	s_and_saveexec_b64 s[20:21], s[40:41]
	ds_write_b32 v208, v218 offset:41088
	s_or_b64 exec, exec, s[20:21]
	v_sub_f32_e32 v81, v81, v177
	v_sub_f32_e32 v80, v80, v177
	v_sub_f32_e32 v79, v79, v177
	v_sub_f32_e32 v78, v78, v177
	v_sub_f32_e32 v77, v77, v177
	v_sub_f32_e32 v76, v76, v177
	v_sub_f32_e32 v75, v75, v177
	v_sub_f32_e32 v74, v74, v177
	v_sub_f32_e32 v73, v73, v177
	v_sub_f32_e32 v72, v72, v177
	v_sub_f32_e32 v71, v71, v177
	v_sub_f32_e32 v70, v70, v177
	v_sub_f32_e32 v69, v69, v177
	v_sub_f32_e32 v68, v68, v177
	v_sub_f32_e32 v67, v67, v177
	v_sub_f32_e32 v66, v66, v177
	v_sub_f32_e32 v230, 0x40e00000, v217
	v_mov_b32_e32 v231, v230
	v_mov_b32_e32 v232, v230
	v_mov_b32_e32 v233, v230
	v_mov_b32_e32 v234, v230
	v_mov_b32_e32 v235, v230
	v_mov_b32_e32 v236, v230
	v_mov_b32_e32 v237, v230
	v_mov_b32_e32 v238, v230
	v_mov_b32_e32 v239, v230
	v_mov_b32_e32 v240, v230
	v_mov_b32_e32 v241, v230
	v_mov_b32_e32 v242, v230
	v_mov_b32_e32 v243, v230
	v_mov_b32_e32 v244, v230
	v_mov_b32_e32 v245, v230
	v_add_u32_e32 v0, v187, v207
	s_waitcnt lgkmcnt(0)
	ds_read_b128 v[98:101], v0 offset:41184
	ds_read_b128 v[102:105], v0 offset:41152
	ds_read_b128 v[106:109], v0 offset:41120
	ds_read_b128 v[110:113], v0 offset:41088
	s_waitcnt lgkmcnt(0)
	v_pk_mul_f32 v[62:63], v[62:63], v[98:99]
	v_pk_mul_f32 v[58:59], v[58:59], v[102:103]
	v_pk_mul_f32 v[54:55], v[54:55], v[106:107]
	v_pk_mul_f32 v[64:65], v[64:65], v[100:101]
	v_pk_mul_f32 v[60:61], v[60:61], v[104:105]
	v_pk_mul_f32 v[56:57], v[56:57], v[108:109]
	v_pk_mul_f32 v[52:53], v[52:53], v[112:113]
	v_pk_mul_f32 v[50:51], v[50:51], v[110:111]
	v_pk_mul_f32 v[46:47], v[46:47], v[98:99]
	v_pk_mul_f32 v[42:43], v[42:43], v[102:103]
	v_pk_mul_f32 v[38:39], v[38:39], v[106:107]
	v_pk_mul_f32 v[48:49], v[48:49], v[100:101]
	v_pk_mul_f32 v[44:45], v[44:45], v[104:105]
	v_pk_mul_f32 v[40:41], v[40:41], v[108:109]
	v_pk_mul_f32 v[36:37], v[36:37], v[112:113]
	v_pk_mul_f32 v[34:35], v[34:35], v[110:111]
	v_pk_mul_f32 v[30:31], v[30:31], v[98:99]
	v_pk_mul_f32 v[26:27], v[26:27], v[102:103]
	v_pk_mul_f32 v[22:23], v[22:23], v[106:107]
	v_pk_mul_f32 v[32:33], v[32:33], v[100:101]
	v_pk_mul_f32 v[28:29], v[28:29], v[104:105]
	v_pk_mul_f32 v[24:25], v[24:25], v[108:109]
	v_pk_mul_f32 v[20:21], v[20:21], v[112:113]
	v_pk_mul_f32 v[18:19], v[18:19], v[110:111]
	v_pk_mul_f32 v[14:15], v[14:15], v[98:99]
	v_pk_mul_f32 v[10:11], v[10:11], v[102:103]
	v_pk_mul_f32 v[6:7], v[6:7], v[106:107]
	v_pk_mul_f32 v[16:17], v[16:17], v[100:101]
	v_pk_mul_f32 v[12:13], v[12:13], v[104:105]
	v_pk_mul_f32 v[8:9], v[8:9], v[108:109]
	v_pk_mul_f32 v[4:5], v[4:5], v[112:113]
	v_pk_mul_f32 v[2:3], v[2:3], v[110:111]
	s_branch .Lmla_h3_cont
.Lmla_h4_newmax:
	v_add_f32_e32 v0, 0xc0e00000, v177
	v_max_f32_e32 v177, 0, v0
	v_exp_f32_e64 v221, -v177
	v_add_f32_e32 v217, v217, v177
	v_sub_f32_e32 v129, v129, v177
	v_sub_f32_e32 v128, v128, v177
	v_sub_f32_e32 v127, v127, v177
	v_sub_f32_e32 v126, v126, v177
	v_sub_f32_e32 v125, v125, v177
	v_sub_f32_e32 v124, v124, v177
	v_sub_f32_e32 v123, v123, v177
	v_sub_f32_e32 v122, v122, v177
	v_sub_f32_e32 v121, v121, v177
	v_sub_f32_e32 v120, v120, v177
	v_sub_f32_e32 v119, v119, v177
	v_sub_f32_e32 v118, v118, v177
	v_sub_f32_e32 v117, v117, v177
	v_sub_f32_e32 v116, v116, v177
	v_sub_f32_e32 v115, v115, v177
	v_sub_f32_e32 v114, v114, v177
	s_and_saveexec_b64 s[20:21], s[40:41]
	ds_write_b32 v208, v221 offset:41088
	s_or_b64 exec, exec, s[20:21]
	v_sub_f32_e32 v113, v113, v177
	v_sub_f32_e32 v112, v112, v177
	v_sub_f32_e32 v111, v111, v177
	v_sub_f32_e32 v110, v110, v177
	v_sub_f32_e32 v109, v109, v177
	v_sub_f32_e32 v108, v108, v177
	v_sub_f32_e32 v107, v107, v177
	v_sub_f32_e32 v106, v106, v177
	v_sub_f32_e32 v105, v105, v177
	v_sub_f32_e32 v104, v104, v177
	v_sub_f32_e32 v103, v103, v177
	v_sub_f32_e32 v102, v102, v177
	v_sub_f32_e32 v101, v101, v177
	v_sub_f32_e32 v100, v100, v177
	v_sub_f32_e32 v99, v99, v177
	v_sub_f32_e32 v98, v98, v177
	v_sub_f32_e32 v230, 0x40e00000, v217
	v_mov_b32_e32 v231, v230
	v_mov_b32_e32 v232, v230
	v_mov_b32_e32 v233, v230
	v_mov_b32_e32 v234, v230
	v_mov_b32_e32 v235, v230
	v_mov_b32_e32 v236, v230
	v_mov_b32_e32 v237, v230
	v_mov_b32_e32 v238, v230
	v_mov_b32_e32 v239, v230
	v_mov_b32_e32 v240, v230
	v_mov_b32_e32 v241, v230
	v_mov_b32_e32 v242, v230
	v_mov_b32_e32 v243, v230
	v_mov_b32_e32 v244, v230
	v_mov_b32_e32 v245, v230
	v_add_u32_e32 v0, v187, v207
	s_waitcnt lgkmcnt(0)
	ds_read_b128 v[66:69], v0 offset:41184
	ds_read_b128 v[70:73], v0 offset:41152
	ds_read_b128 v[74:77], v0 offset:41120
	ds_read_b128 v[78:81], v0 offset:41088
	s_waitcnt lgkmcnt(0)
	v_pk_mul_f32 v[62:63], v[62:63], v[66:67]
	v_pk_mul_f32 v[58:59], v[58:59], v[70:71]
	v_pk_mul_f32 v[54:55], v[54:55], v[74:75]
	v_pk_mul_f32 v[64:65], v[64:65], v[68:69]
	v_pk_mul_f32 v[60:61], v[60:61], v[72:73]
	v_pk_mul_f32 v[56:57], v[56:57], v[76:77]
	v_pk_mul_f32 v[52:53], v[52:53], v[80:81]
	v_pk_mul_f32 v[50:51], v[50:51], v[78:79]
	v_pk_mul_f32 v[46:47], v[46:47], v[66:67]
	v_pk_mul_f32 v[42:43], v[42:43], v[70:71]
	v_pk_mul_f32 v[38:39], v[38:39], v[74:75]
	v_pk_mul_f32 v[48:49], v[48:49], v[68:69]
	v_pk_mul_f32 v[44:45], v[44:45], v[72:73]
	v_pk_mul_f32 v[40:41], v[40:41], v[76:77]
	v_pk_mul_f32 v[36:37], v[36:37], v[80:81]
	v_pk_mul_f32 v[34:35], v[34:35], v[78:79]
	v_pk_mul_f32 v[30:31], v[30:31], v[66:67]
	v_pk_mul_f32 v[26:27], v[26:27], v[70:71]
	v_pk_mul_f32 v[22:23], v[22:23], v[74:75]
	v_pk_mul_f32 v[32:33], v[32:33], v[68:69]
	v_pk_mul_f32 v[28:29], v[28:29], v[72:73]
	v_pk_mul_f32 v[24:25], v[24:25], v[76:77]
	v_pk_mul_f32 v[20:21], v[20:21], v[80:81]
	v_pk_mul_f32 v[18:19], v[18:19], v[78:79]
	v_pk_mul_f32 v[14:15], v[14:15], v[66:67]
	v_pk_mul_f32 v[10:11], v[10:11], v[70:71]
	v_pk_mul_f32 v[6:7], v[6:7], v[74:75]
	v_pk_mul_f32 v[16:17], v[16:17], v[68:69]
	v_pk_mul_f32 v[12:13], v[12:13], v[72:73]
	v_pk_mul_f32 v[8:9], v[8:9], v[76:77]
	v_pk_mul_f32 v[4:5], v[4:5], v[80:81]
	v_pk_mul_f32 v[2:3], v[2:3], v[78:79]
	s_branch .Lmla_h4_cont
; __device__ __forceinline__ void partialSM9(f32x16& p0, f32x16& p1, float& m_run, float& alpha, const float thr2) {
;   float pmax = p0[0];
; #pragma unroll
;   for (int r = 1; r < 16; ++r) pmax = fmaxf(pmax, p0[r]);
; #pragma unroll
;   for (int r = 0; r < 16; ++r) pmax = fmaxf(pmax, p1[r]);
;   { auto rr = __builtin_amdgcn_permlane32_swap(__float_as_uint(pmax), __float_as_uint(pmax), false, false);
;     pmax = fmaxf(__uint_as_float(rr[0]), __uint_as_float(rr[1])); }
;   if (__builtin_expect(__all(pmax <= 7.0f + thr2), 1)) { alpha = 1.f; }
;   else { const float delta = fmaxf(pmax - 7.0f, 0.f); alpha = __builtin_amdgcn_exp2f(-delta); m_run += delta;
; #pragma unroll
;     for (int r = 0; r < 16; ++r) { p0[r] -= delta; p1[r] -= delta; } }
; }
.Lmla_h5_newmax:
	v_add_f32_e32 v0, 0xc0e00000, v177
	v_max_f32_e32 v177, 0, v0
	v_exp_f32_e64 v218, -v177
	v_add_f32_e32 v217, v217, v177
	v_sub_f32_e32 v97, v97, v177
	v_sub_f32_e32 v96, v96, v177
	v_sub_f32_e32 v95, v95, v177
	v_sub_f32_e32 v94, v94, v177
	v_sub_f32_e32 v93, v93, v177
	v_sub_f32_e32 v92, v92, v177
	v_sub_f32_e32 v91, v91, v177
	v_sub_f32_e32 v90, v90, v177
	v_sub_f32_e32 v89, v89, v177
	v_sub_f32_e32 v88, v88, v177
	v_sub_f32_e32 v87, v87, v177
	v_sub_f32_e32 v86, v86, v177
	v_sub_f32_e32 v85, v85, v177
	v_sub_f32_e32 v84, v84, v177
	v_sub_f32_e32 v83, v83, v177
	v_sub_f32_e32 v82, v82, v177
	s_and_saveexec_b64 s[20:21], s[40:41]
	ds_write_b32 v208, v218 offset:41088
	s_or_b64 exec, exec, s[20:21]
	v_sub_f32_e32 v81, v81, v177
	v_sub_f32_e32 v80, v80, v177
	v_sub_f32_e32 v79, v79, v177
	v_sub_f32_e32 v78, v78, v177
	v_sub_f32_e32 v77, v77, v177
	v_sub_f32_e32 v76, v76, v177
	v_sub_f32_e32 v75, v75, v177
	v_sub_f32_e32 v74, v74, v177
	v_sub_f32_e32 v73, v73, v177
	v_sub_f32_e32 v72, v72, v177
	v_sub_f32_e32 v71, v71, v177
	v_sub_f32_e32 v70, v70, v177
	v_sub_f32_e32 v69, v69, v177
	v_sub_f32_e32 v68, v68, v177
	v_sub_f32_e32 v67, v67, v177
	v_sub_f32_e32 v66, v66, v177
	v_sub_f32_e32 v230, 0x40e00000, v217
	v_mov_b32_e32 v231, v230
	v_mov_b32_e32 v232, v230
	v_mov_b32_e32 v233, v230
	v_mov_b32_e32 v234, v230
	v_mov_b32_e32 v235, v230
	v_mov_b32_e32 v236, v230
	v_mov_b32_e32 v237, v230
	v_mov_b32_e32 v238, v230
	v_mov_b32_e32 v239, v230
	v_mov_b32_e32 v240, v230
	v_mov_b32_e32 v241, v230
	v_mov_b32_e32 v242, v230
	v_mov_b32_e32 v243, v230
	v_mov_b32_e32 v244, v230
	v_mov_b32_e32 v245, v230
	v_add_u32_e32 v0, v187, v207
	s_waitcnt lgkmcnt(0)
	ds_read_b128 v[98:101], v0 offset:41184
	ds_read_b128 v[102:105], v0 offset:41152
	ds_read_b128 v[106:109], v0 offset:41120
	ds_read_b128 v[110:113], v0 offset:41088
	s_waitcnt lgkmcnt(0)
	v_pk_mul_f32 v[62:63], v[62:63], v[98:99]
	v_pk_mul_f32 v[58:59], v[58:59], v[102:103]
	v_pk_mul_f32 v[54:55], v[54:55], v[106:107]
	v_pk_mul_f32 v[64:65], v[64:65], v[100:101]
	v_pk_mul_f32 v[60:61], v[60:61], v[104:105]
	v_pk_mul_f32 v[56:57], v[56:57], v[108:109]
	v_pk_mul_f32 v[52:53], v[52:53], v[112:113]
	v_pk_mul_f32 v[50:51], v[50:51], v[110:111]
	v_pk_mul_f32 v[46:47], v[46:47], v[98:99]
	v_pk_mul_f32 v[42:43], v[42:43], v[102:103]
	v_pk_mul_f32 v[38:39], v[38:39], v[106:107]
	v_pk_mul_f32 v[48:49], v[48:49], v[100:101]
	v_pk_mul_f32 v[44:45], v[44:45], v[104:105]
	v_pk_mul_f32 v[40:41], v[40:41], v[108:109]
	v_pk_mul_f32 v[36:37], v[36:37], v[112:113]
	v_pk_mul_f32 v[34:35], v[34:35], v[110:111]
	v_pk_mul_f32 v[30:31], v[30:31], v[98:99]
	v_pk_mul_f32 v[26:27], v[26:27], v[102:103]
	v_pk_mul_f32 v[22:23], v[22:23], v[106:107]
	v_pk_mul_f32 v[32:33], v[32:33], v[100:101]
	v_pk_mul_f32 v[28:29], v[28:29], v[104:105]
	v_pk_mul_f32 v[24:25], v[24:25], v[108:109]
	v_pk_mul_f32 v[20:21], v[20:21], v[112:113]
	v_pk_mul_f32 v[18:19], v[18:19], v[110:111]
	v_pk_mul_f32 v[14:15], v[14:15], v[98:99]
	v_pk_mul_f32 v[10:11], v[10:11], v[102:103]
	v_pk_mul_f32 v[6:7], v[6:7], v[106:107]
	v_pk_mul_f32 v[16:17], v[16:17], v[100:101]
	v_pk_mul_f32 v[12:13], v[12:13], v[104:105]
	v_pk_mul_f32 v[8:9], v[8:9], v[108:109]
	v_pk_mul_f32 v[4:5], v[4:5], v[112:113]
	v_pk_mul_f32 v[2:3], v[2:3], v[110:111]
	s_branch .Lmla_h5_cont
.Lmla_p0_newmax:
	v_add_f32_e32 v0, 0xc0e00000, v177
	v_max_f32_e32 v177, 0, v0
	v_exp_f32_e64 v221, -v177
	v_add_f32_e32 v217, v217, v177
	v_sub_f32_e32 v129, v129, v177
	v_sub_f32_e32 v128, v128, v177
	v_sub_f32_e32 v127, v127, v177
	v_sub_f32_e32 v126, v126, v177
	v_sub_f32_e32 v125, v125, v177
	v_sub_f32_e32 v124, v124, v177
	v_sub_f32_e32 v123, v123, v177
	v_sub_f32_e32 v122, v122, v177
	v_sub_f32_e32 v121, v121, v177
	v_sub_f32_e32 v120, v120, v177
	v_sub_f32_e32 v119, v119, v177
	v_sub_f32_e32 v118, v118, v177
	v_sub_f32_e32 v117, v117, v177
	v_sub_f32_e32 v116, v116, v177
	v_sub_f32_e32 v115, v115, v177
	v_sub_f32_e32 v114, v114, v177
	s_and_saveexec_b64 s[20:21], s[40:41]
	ds_write_b32 v208, v221 offset:41088
	s_or_b64 exec, exec, s[20:21]
	v_sub_f32_e32 v113, v113, v177
	v_sub_f32_e32 v112, v112, v177
	v_sub_f32_e32 v111, v111, v177
	v_sub_f32_e32 v110, v110, v177
	v_sub_f32_e32 v109, v109, v177
	v_sub_f32_e32 v108, v108, v177
	v_sub_f32_e32 v107, v107, v177
	v_sub_f32_e32 v106, v106, v177
	v_sub_f32_e32 v105, v105, v177
	v_sub_f32_e32 v104, v104, v177
	v_sub_f32_e32 v103, v103, v177
	v_sub_f32_e32 v102, v102, v177
	v_sub_f32_e32 v101, v101, v177
	v_sub_f32_e32 v100, v100, v177
	v_sub_f32_e32 v99, v99, v177
	v_sub_f32_e32 v98, v98, v177
	v_sub_f32_e32 v230, 0x40e00000, v217
	v_mov_b32_e32 v231, v230
	v_mov_b32_e32 v232, v230
	v_mov_b32_e32 v233, v230
	v_mov_b32_e32 v234, v230
	v_mov_b32_e32 v235, v230
	v_mov_b32_e32 v236, v230
	v_mov_b32_e32 v237, v230
	v_mov_b32_e32 v238, v230
	v_mov_b32_e32 v239, v230
	v_mov_b32_e32 v240, v230
	v_mov_b32_e32 v241, v230
	v_mov_b32_e32 v242, v230
	v_mov_b32_e32 v243, v230
	v_mov_b32_e32 v244, v230
	v_mov_b32_e32 v245, v230
	v_add_u32_e32 v0, v187, v207
	s_waitcnt lgkmcnt(0)
	ds_read_b128 v[66:69], v0 offset:41184
	ds_read_b128 v[70:73], v0 offset:41152
	ds_read_b128 v[74:77], v0 offset:41120
	ds_read_b128 v[78:81], v0 offset:41088
	s_waitcnt lgkmcnt(0)
	v_pk_mul_f32 v[62:63], v[62:63], v[66:67]
	v_pk_mul_f32 v[58:59], v[58:59], v[70:71]
	v_pk_mul_f32 v[54:55], v[54:55], v[74:75]
	v_pk_mul_f32 v[64:65], v[64:65], v[68:69]
	v_pk_mul_f32 v[60:61], v[60:61], v[72:73]
	v_pk_mul_f32 v[56:57], v[56:57], v[76:77]
	v_pk_mul_f32 v[52:53], v[52:53], v[80:81]
	v_pk_mul_f32 v[50:51], v[50:51], v[78:79]
	v_pk_mul_f32 v[46:47], v[46:47], v[66:67]
	v_pk_mul_f32 v[42:43], v[42:43], v[70:71]
	v_pk_mul_f32 v[38:39], v[38:39], v[74:75]
	v_pk_mul_f32 v[48:49], v[48:49], v[68:69]
	v_pk_mul_f32 v[44:45], v[44:45], v[72:73]
	v_pk_mul_f32 v[40:41], v[40:41], v[76:77]
	v_pk_mul_f32 v[36:37], v[36:37], v[80:81]
	v_pk_mul_f32 v[34:35], v[34:35], v[78:79]
	v_pk_mul_f32 v[30:31], v[30:31], v[66:67]
	v_pk_mul_f32 v[26:27], v[26:27], v[70:71]
	v_pk_mul_f32 v[22:23], v[22:23], v[74:75]
	v_pk_mul_f32 v[32:33], v[32:33], v[68:69]
	v_pk_mul_f32 v[28:29], v[28:29], v[72:73]
	v_pk_mul_f32 v[24:25], v[24:25], v[76:77]
	v_pk_mul_f32 v[20:21], v[20:21], v[80:81]
	v_pk_mul_f32 v[18:19], v[18:19], v[78:79]
	v_pk_mul_f32 v[14:15], v[14:15], v[66:67]
	v_pk_mul_f32 v[10:11], v[10:11], v[70:71]
	v_pk_mul_f32 v[6:7], v[6:7], v[74:75]
	v_pk_mul_f32 v[16:17], v[16:17], v[68:69]
	v_pk_mul_f32 v[12:13], v[12:13], v[72:73]
	v_pk_mul_f32 v[8:9], v[8:9], v[76:77]
	v_pk_mul_f32 v[4:5], v[4:5], v[80:81]
	v_pk_mul_f32 v[2:3], v[2:3], v[78:79]
	s_branch .Lmla_p0_cont

; #define RESC(a) do { if (__any((a) < 1.f)) { if (hi == 0) al_l[r32] = (a); asm volatile("s_waitcnt lgkmcnt(0)" ::: "memory"); \
;     _Pragma("unroll") for (int d = 0; d < 4; ++d) _Pragma("unroll") for (int r = 0; r < 16; ++r) o[d][r] *= al_l[crow(r, hi)]; } } while (0)
; __device__ __forceinline__ v8i32 cat8(v4i32 a, v4i32 b) { return (v8i32){a[0], a[1], a[2], a[3], b[0], b[1], b[2], b[3]}; }
; #define RESC(a) do { if (__any((a) < 1.f)) { if (hi == 0) al_l[r32] = (a); asm volatile("s_waitcnt lgkmcnt(0)" ::: "memory"); \
;     _Pragma("unroll") for (int d = 0; d < 4; ++d) _Pragma("unroll") for (int r = 0; r < 16; ++r) o[d][r] *= al_l[crow(r, hi)]; } } while (0)
; __device__ __forceinline__ void qkt9(f32x16& p0, f32x16& p1, const char* Kn, const char* Kr, const v8i32* qf, const float init, int r32, int hi) {
; #pragma unroll
;   for (int r = 0; r < 16; ++r) { p0[r] = init; p1[r] = init; }
; #pragma unroll
;   for (int s = 0; s < 2; ++s) { const int c0 = s * 4 + hi * 2;
;     const v8i32 a0 = cat8(*reinterpret_cast<const v4i32*>(Kn + KN8SW(r32, c0)), *reinterpret_cast<const v4i32*>(Kn + KN8SW(r32, c0 + 1)));
;     const v8i32 a1 = cat8(*reinterpret_cast<const v4i32*>(Kn + 4096 + KN8SW(r32, c0)), *reinterpret_cast<const v4i32*>(Kn + 4096 + KN8SW(r32, c0 + 1)));
;     p0 = __builtin_amdgcn_mfma_scale_f32_32x32x64_f8f6f4(a0, qf[s], p0, 0, 0, 0, 127, 0, 124);
;     p1 = __builtin_amdgcn_mfma_scale_f32_32x32x64_f8f6f4(a1, qf[s], p1, 0, 0, 0, 127, 0, 124); }
;   { const int c0 = hi * 2;
;     const v8i32 a0 = cat8(*reinterpret_cast<const v4i32*>(Kr + KR8SW(r32, c0)), *reinterpret_cast<const v4i32*>(Kr + KR8SW(r32, c0 + 1)));
;     const v8i32 a1 = cat8(*reinterpret_cast<const v4i32*>(Kr + 2048 + KR8SW(r32, c0)), *reinterpret_cast<const v4i32*>(Kr + 2048 + KR8SW(r32, c0 + 1)));
;     p0 = __builtin_amdgcn_mfma_scale_f32_32x32x64_f8f6f4(a0, qf[2], p0, 0, 0, 0, 127, 0, 124);
;     p1 = __builtin_amdgcn_mfma_scale_f32_32x32x64_f8f6f4(a1, qf[2], p1, 0, 0, 0, 127, 0, 124); }
; }
; __device__ __forceinline__ void attn_unit7(const unsigned char* __restrict__ Q8, int ldq, const unsigned char* __restrict__ Kn8, int ldk, const unsigned char* __restrict__ Kr8, ...
;     ...
;   qkt9(pB0, pB1, Kn_lds + 8192, Kr_lds + 4096, qf, 7.0f - m_reg, r32, hi);
;   finishSM9(pA0, pA1, alA, l_reg, p8);
;   pv8(o, Vt_lds, p8, r32, hi); partialSM9(pB0, pB1, m_reg, alB, thr_raw);
;   RESC(alB);
.LBB0_1343:
	ds_read_b128 v[114:117], v215 offset:16384
	ds_read_b128 v[118:121], v216 offset:16384
	ds_read_b128 v[154:157], v215 offset:20480
	ds_read_b128 v[158:161], v216 offset:20480
	v_sub_f32_e32 v98, 0x40e00000, v217
	v_mov_b32_e32 v99, v98
	v_mov_b32_e32 v100, v98
	v_mov_b32_e32 v101, v98
	v_mov_b32_e32 v102, v98
	v_mov_b32_e32 v103, v98
	v_mov_b32_e32 v104, v98
	v_mov_b32_e32 v105, v98
	v_mov_b32_e32 v106, v98
	v_mov_b32_e32 v107, v98
	v_mov_b32_e32 v108, v98
	v_mov_b32_e32 v109, v98
	v_mov_b32_e32 v110, v98
	v_mov_b32_e32 v111, v98
	v_mov_b32_e32 v112, v98
	v_mov_b32_e32 v113, v98
	v_exp_f32_e32 v162, v91
	v_exp_f32_e32 v163, v95
	s_waitcnt lgkmcnt(2)
	v_mfma_scale_f32_32x32x64_f8f6f4 v[114:129], v[114:121], v[146:153], v[98:113], v194, v193 op_sel_hi:[0,0,0]
	v_exp_f32_e32 v164, v81
	s_waitcnt lgkmcnt(0)
	v_mfma_scale_f32_32x32x64_f8f6f4 v[98:113], v[154:161], v[146:153], v[98:113], v194, v193 op_sel_hi:[0,0,0]
	ds_read_b128 v[146:149], v213 offset:16384
	ds_read_b128 v[150:153], v214 offset:16384
	ds_read_b128 v[154:157], v213 offset:20480
	ds_read_b128 v[158:161], v214 offset:20480
	s_waitcnt lgkmcnt(2)
	v_mfma_scale_f32_32x32x64_f8f6f4 v[114:129], v[146:153], v[138:145], v[114:129], v194, v193 op_sel_hi:[0,0,0]
	s_waitcnt lgkmcnt(0)
	v_mfma_scale_f32_32x32x64_f8f6f4 v[98:113], v[154:161], v[138:145], v[98:113], v194, v193 op_sel_hi:[0,0,0]
	ds_read_b128 v[138:141], v185 offset:32768
	ds_read_b128 v[142:145], v186 offset:32768
	ds_read_b128 v[146:149], v185 offset:34816
	ds_read_b128 v[150:153], v186 offset:34816
	v_exp_f32_e32 v160, v83
	v_exp_f32_e32 v154, v86
	v_exp_f32_e32 v161, v87
	v_exp_f32_e32 v158, v90
	v_exp_f32_e32 v159, v94
	v_exp_f32_e32 v157, v97
	v_exp_f32_e32 v155, v75
	v_exp_f32_e32 v156, v79
	s_waitcnt lgkmcnt(2)
	v_mfma_scale_f32_32x32x64_f8f6f4 v[114:129], v[138:145], v[130:137], v[114:129], v194, v193 op_sel_hi:[0,0,0]
	v_exp_f32_e32 v141, v82
	v_exp_f32_e32 v143, v66
	v_exp_f32_e32 v145, v88
	v_exp_f32_e32 v139, v93
	v_add_f32_e32 v66, 0, v141
	v_add_f32_e32 v66, v160, v66
	v_exp_f32_e32 v138, v69
	v_exp_f32_e32 v144, v70
	v_exp_f32_e32 v142, v72
	v_exp_f32_e32 v140, v77
	s_nop 9
	v_max_f32_e32 v165, v114, v114
	s_waitcnt lgkmcnt(0)
	v_mfma_scale_f32_32x32x64_f8f6f4 v[98:113], v[146:153], v[130:137], v[98:113], v194, v193 op_sel_hi:[0,0,0]
	v_exp_f32_e32 v133, v84
	v_exp_f32_e32 v137, v85
	v_exp_f32_e32 v153, v89
	v_exp_f32_e32 v135, v92
	v_add_f32_e32 v66, v133, v66
	v_add_f32_e32 v66, v137, v66
	v_add_f32_e32 v66, v154, v66
	v_add_f32_e32 v66, v161, v66
	v_add_f32_e32 v66, v145, v66
	v_add_f32_e32 v66, v153, v66
	v_add_f32_e32 v66, v158, v66
	v_add_f32_e32 v66, v162, v66
	v_exp_f32_e32 v150, v96
	v_add_f32_e32 v66, v135, v66
	v_add_f32_e32 v66, v139, v66
	v_add_f32_e32 v66, v159, v66
	v_exp_f32_e32 v151, v67
	v_add_f32_e32 v66, v163, v66
	v_exp_f32_e32 v134, v68
	v_add_f32_e32 v66, v150, v66
	v_add_f32_e32 v66, v157, v66
	v_add_f32_e32 v66, v143, v66
	v_exp_f32_e32 v152, v71
	v_add_f32_e32 v66, v151, v66
	v_add_f32_e32 v66, v134, v66
	v_exp_f32_e32 v147, v73
	v_add_f32_e32 v66, v138, v66
	v_max_f32_e32 v132, v115, v115
	v_exp_f32_e32 v148, v74
	v_add_f32_e32 v66, v144, v66
	v_max_f32_e32 v132, v165, v132
	v_add_f32_e32 v66, v152, v66
	v_max3_f32 v132, v132, v116, v117
	v_exp_f32_e32 v136, v76
	v_add_f32_e32 v66, v142, v66
	v_max3_f32 v132, v132, v118, v119
	v_add_f32_e32 v66, v147, v66
	v_max3_f32 v132, v132, v120, v121
	v_exp_f32_e32 v149, v78
	v_add_f32_e32 v66, v148, v66
	v_max3_f32 v132, v132, v122, v123
	v_add_f32_e32 v66, v155, v66
	v_max3_f32 v132, v132, v124, v125
	v_exp_f32_e32 v146, v80
	v_add_f32_e32 v66, v136, v66
	v_max3_f32 v132, v132, v126, v127
	v_add_f32_e32 v66, v140, v66
	v_max3_f32 v132, v132, v128, v129
	v_add_f32_e32 v66, v149, v66
	v_max3_f32 v132, v132, v98, v99
	v_add_f32_e32 v66, v156, v66
	v_max3_f32 v132, v132, v100, v101
	v_add_f32_e32 v66, v146, v66
	v_max3_f32 v132, v132, v102, v103
	v_add_f32_e32 v130, v164, v66
	ds_read_b128 v[90:93], v185 offset:43008
	ds_read_b128 v[94:97], v186 offset:43008
	ds_read_b128 v[82:85], v185 offset:45056
	ds_read_b128 v[86:89], v186 offset:45056
	ds_read_b128 v[74:77], v185 offset:47104
	ds_read_b128 v[78:81], v186 offset:47104
	ds_read_b128 v[66:69], v185 offset:49152
	ds_read_b128 v[70:73], v186 offset:49152
	v_max3_f32 v132, v132, v104, v105
	v_max3_f32 v132, v132, v106, v107
	v_max3_f32 v132, v132, v108, v109
	v_max3_f32 v132, v132, v110, v111
	v_max3_f32 v132, v132, v112, v113
	v_mov_b32_e32 v165, v132
	s_nop 1
	v_permlane32_swap_b32_e32 v132, v165
	v_max_f32_e32 v165, v165, v165
	v_max_f32_e32 v132, v132, v132
	v_max_f32_e32 v165, v132, v165
	v_mov_b32_e32 v131, v130
	v_cmp_ge_f32_e32 vcc, s90, v165
	s_nop 0
	v_permlane32_swap_b32_e32 v130, v131
	v_mov_b32_e32 v132, 1.0
	s_cmp_eq_u64 vcc, exec
	s_cbranch_scc0 .LBB0_1351

; __device__ __forceinline__ void finishSM9(f32x16& p0, f32x16& p1, float alpha, float& l_reg, v8i32& p8) {
; #pragma unroll
;   for (int r = 0; r < 16; ++r) { p0[r] = __builtin_amdgcn_exp2f(p0[r]); p1[r] = __builtin_amdgcn_exp2f(p1[r]); }
;   float ps = 0;
; #pragma unroll
;   for (int r = 0; r < 16; ++r) ps += p0[r];
; #pragma unroll
;   for (int r = 0; r < 16; ++r) ps += p1[r];
;   { auto rr = __builtin_amdgcn_permlane32_swap(__float_as_uint(ps), __float_as_uint(ps), false, false);
;     ps = __uint_as_float(rr[0]) + __uint_as_float(rr[1]); }
;   l_reg = l_reg * alpha + ps;
; __device__ __forceinline__ void attn_unit7(const unsigned char* __restrict__ Q8, int ldq, const unsigned char* __restrict__ Kn8, int ldk, const unsigned char* __restrict__ Kr8, ...
;     ...
;   finishSM9(pB0, pB1, alB, l_reg, p8);
;   pv8(o, Vt_lds + 8192, p8, r32, hi);
;   if (hi == 0) li_l[r32] = l_reg; asm volatile("s_waitcnt lgkmcnt(0)" ::: "memory");
.LBB0_1348:
	v_exp_f32_e32 v139, v114
	v_exp_f32_e32 v141, v115
	v_exp_f32_e32 v114, v116
	v_exp_f32_e32 v116, v117
	v_exp_f32_e32 v140, v118
	v_add_f32_e32 v66, 0, v139
	v_exp_f32_e32 v142, v119
	v_add_f32_e32 v66, v141, v66
	v_exp_f32_e32 v119, v120
	v_add_f32_e32 v66, v114, v66
	v_exp_f32_e32 v138, v121
	v_add_f32_e32 v66, v116, v66
	v_exp_f32_e32 v120, v122
	v_add_f32_e32 v66, v140, v66
	v_exp_f32_e32 v122, v123
	v_add_f32_e32 v66, v142, v66
	v_exp_f32_e32 v133, v98
	v_exp_f32_e32 v98, v124
	v_add_f32_e32 v66, v119, v66
	v_exp_f32_e32 v115, v100
	v_exp_f32_e32 v100, v125
	v_add_f32_e32 v66, v138, v66
	v_exp_f32_e32 v121, v126
	v_add_f32_e32 v66, v120, v66
	v_exp_f32_e32 v118, v104
	v_exp_f32_e32 v104, v110
	v_exp_f32_e32 v110, v127
	v_add_f32_e32 v66, v122, v66
	v_exp_f32_e32 v135, v105
	v_exp_f32_e32 v105, v128
	v_add_f32_e32 v66, v98, v66
	v_exp_f32_e32 v117, v101
	v_exp_f32_e32 v101, v109
	v_exp_f32_e32 v109, v129
	v_add_f32_e32 v66, v100, v66
	v_add_f32_e32 v66, v121, v66
	v_exp_f32_e32 v136, v99
	v_add_f32_e32 v66, v110, v66
	v_add_f32_e32 v66, v105, v66
	v_add_f32_e32 v66, v109, v66
	v_exp_f32_e32 v134, v102
	v_add_f32_e32 v66, v133, v66
	v_exp_f32_e32 v137, v103
	v_add_f32_e32 v66, v136, v66
	v_add_f32_e32 v66, v115, v66
	v_add_f32_e32 v66, v117, v66
	v_exp_f32_e32 v103, v106
	v_add_f32_e32 v66, v134, v66
	v_exp_f32_e32 v107, v107
	v_add_f32_e32 v66, v137, v66
	v_exp_f32_e32 v99, v108
	v_add_f32_e32 v66, v118, v66
	v_add_f32_e32 v66, v135, v66
	v_add_f32_e32 v66, v103, v66
	v_exp_f32_e32 v108, v111
	v_add_f32_e32 v66, v107, v66
	v_exp_f32_e32 v102, v112
	v_add_f32_e32 v66, v99, v66
	v_add_f32_e32 v66, v101, v66
	v_add_f32_e32 v66, v104, v66
	v_add_f32_e32 v66, v108, v66
	v_add_f32_e32 v111, v102, v66
	ds_read_b128 v[90:93], v185 offset:0
	ds_read_b128 v[82:85], v185 offset:2048
	ds_read_b128 v[94:97], v186 offset:0
	ds_read_b128 v[86:89], v186 offset:2048
	ds_read_b128 v[74:77], v185 offset:4096
	ds_read_b128 v[66:69], v185 offset:6144
	ds_read_b128 v[78:81], v186 offset:4096
	ds_read_b128 v[70:73], v186 offset:6144
	v_exp_f32_e32 v106, v113
	s_nop 0
	v_add_f32_e32 v111, v106, v111
	v_mov_b32_e32 v112, v111
	s_nop 1
	v_permlane32_swap_b32_e32 v111, v112
	s_and_saveexec_b64 s[16:17], s[40:41]
	s_cbranch_execz .LBB0_1310
	v_add_f32_e32 v113, v130, v131
	v_fmac_f32_e32 v113, v209, v0
	v_add_f32_e32 v0, v111, v112
	v_fmac_f32_e32 v0, v113, v132
	ds_write_b32 v208, v0 offset:40960
	s_branch .LBB0_1310
